# K-loop heads of the six GEMM phases aligned to 64 bytes (code placement)
# speedup vs baseline: 1.0019x; 1.0019x over previous
; #define PG8_STAGE(bufoff, gbase, voff) do { _Pragma("unroll") for (int _i = 0; _i < 2; ++_i) \
;         __builtin_amdgcn_global_load_lds((const unsigned*)((const char*)(gbase) + (voff)[_i]), (PG8_LAS unsigned*)(lds + (bufoff) + ldsw + _i * 8192), 16, 0, 0); } while (0)
; #define PG8_LDA(dst, b, h) do { _Pragma("unroll") for (int m = 0; m < 4; ++m) _Pragma("unroll") for (int k = 0; k < 2; ++k) dst[m][k] = *(const PG8_LAS bf16x8*)(lds + PG8_SA(b, h) + aoff + m * 2048 + k * 1024); } while (0)
; #define PG8_LDB(dst, b, h) do { _Pragma("unroll") for (int n = 0; n < 2; ++n) _Pragma("unroll") for (int k = 0; k < 2; ++k) dst[n][k] = *(const PG8_LAS bf16x8*)(lds + PG8_SB(b, h) + boff + n * 2048 + k * 1024); } while (0)
; #define PG8_MMA(ai, bj, At, Bt) do { __builtin_amdgcn_s_setprio(1); _Pragma("unroll") for (int m = 0; m < 4; ++m) _Pragma("unroll") for (int n = 0; n < 2; ++n) _Pragma("unroll") for (int k = 0; k < 2; ++k) \
;         acc[ai][bj][m][n] = __builtin_amdgcn_mfma_f32_16x16x32_bf16(Bt[n][k], At[m][k], acc[ai][bj][m][n], 0, 0, 0); __builtin_amdgcn_s_setprio(0); } while (0)
; #define PG8_BAR __builtin_amdgcn_s_barrier()
; template <class Epi, class Sched, bool ALIGN_EPI = false, bool SP2 = false>
; __device__ __forceinline__ void gemm_phase(PG8_LAS unsigned char* lds, const Gemm g, const Sched& S, const Epi& E) {
;     ...
;         const bool has_next = S.next(ui + 1, nxt);
;         const char* nA = has_next ? (const char*)g.A + (size_t)nxt.pm * tstep : cA; const char* nB = has_next ? (const char*)g.Bt + (size_t)nxt.pn * tstep : cB;
;         for (int t = 0; t < nt; t += 2) {
;             const bool last = (t == nt - 2);
;             const char* a1 = cA + (size_t)(t + 1) * kstep;
;             const char* a2 = last ? nA : cA + (size_t)(t + 2) * kstep; const char* b2 = last ? nB : cB + (size_t)(t + 2) * kstep;
;             const char* a3 = a2 + kstep; const char* b3 = b2 + kstep;
;             if (last && has_next) S.a_ready(nxt);
;             if constexpr (SP2) {
;             PG8_LDB(B0, 0, 0); PG8_LDB(B1, 0, 1); PG8_SCHED; PG8_LDA(At, 0, 0); PG8_STAGE(PG8_SA(1, 1), a1 + hstep, voffA);
;             PG8_WAIT_V(8); PG8_WAIT_L(0); PG8_BAR; PG8_MMA(0, 0, At, B0); PG8_MMA(0, 1, At, B1); PG8_BAR; PG8_SCHED;
;             PG8_LDA(At, 0, 1); PG8_STAGE(PG8_SB(0, 0), b2, voffB); PG8_STAGE(PG8_SB(0, 1), b2 + hstep, voffB); PG8_STAGE(PG8_SA(0, 0), a2, voffA);
.LBB0_133:
	s_ashr_i32 s27, s26, 31
	s_lshl_b64 s[28:29], s[26:27], 19
	s_add_u32 s28, s76, s28
	s_addc_u32 s29, s77, s29
	s_and_b64 s[30:31], s[4:5], exec
	s_cselect_b32 s1, s29, s35
	s_cselect_b32 s7, s28, s34
	s_ashr_i32 s15, s14, 31
	s_lshl_b64 s[30:31], s[14:15], 19
	s_add_u32 s30, s24, s30
	s_addc_u32 s31, s25, s31
	s_and_b64 s[38:39], s[4:5], exec
	s_cselect_b32 s15, s31, s37
	s_cselect_b32 s27, s30, s36
	s_add_u32 s34, s34, 0x40080
	s_addc_u32 s35, s35, 0
	s_add_u32 s87, s36, 0x100
	s_addc_u32 s88, s37, 0
	s_mov_b32 s89, -2
	ds_read_b128 v[136:139], v151
	ds_read_b128 v[168:171], v151 offset:1024
	ds_read_b128 v[176:179], v151 offset:2048
	ds_read_b128 v[180:183], v151 offset:3072
	ds_read_b128 v[184:187], v164
	ds_read_b128 v[188:191], v164 offset:1024
	ds_read_b128 v[192:195], v164 offset:2048
	ds_read_b128 v[196:199], v164 offset:3072
	s_add_u32 s36, s34, 0xfffc0080
	s_addc_u32 s37, s35, -1
	s_cmp_eq_u32 s89, 12
	s_cselect_b32 s39, s1, s37
	s_cselect_b32 s38, s7, s36
	s_cselect_b32 s37, s15, s88
	s_cselect_b32 s36, s27, s87
	v_lshl_add_u64 v[228:229], s[34:35], 0, v[128:129]
	s_add_i32 m0, s33, 0xc000
	ds_read_b128 v[200:203], v165
	ds_read_b128 v[204:207], v165 offset:1024
	ds_read_b128 v[208:211], v165 offset:2048
	ds_read_b128 v[212:215], v165 offset:3072
	ds_read_b128 v[216:219], v165 offset:4096
	ds_read_b128 v[220:223], v165 offset:5120
	ds_read_b128 v[224:227], v165 offset:6144
	ds_read_b128 v[240:243], v165 offset:7168
	global_load_lds_dwordx4 v[228:229], off
	v_lshl_add_u64 v[228:229], s[34:35], 0, v[130:131]
	s_add_i32 m0, s33, 0xe000
	s_nop 0
	global_load_lds_dwordx4 v[228:229], off
	s_waitcnt vmcnt(8)
	s_waitcnt lgkmcnt(0)
	s_setprio 1
	s_barrier
	v_mfma_f32_16x16x32_bf16 v[124:127], v[136:139], v[200:203], 0
	v_mfma_f32_16x16x32_bf16 v[116:119], v[176:179], v[200:203], 0
	v_mfma_f32_16x16x32_bf16 v[108:111], v[136:139], v[208:211], 0
	v_mfma_f32_16x16x32_bf16 v[100:103], v[176:179], v[208:211], 0
	v_mfma_f32_16x16x32_bf16 v[92:95], v[136:139], v[216:219], 0
	v_mfma_f32_16x16x32_bf16 v[84:87], v[176:179], v[216:219], 0
	v_mfma_f32_16x16x32_bf16 v[76:79], v[136:139], v[224:227], 0
	v_mfma_f32_16x16x32_bf16 v[68:71], v[176:179], v[224:227], 0
	v_mfma_f32_16x16x32_bf16 v[124:127], v[168:171], v[204:207], v[124:127]
	v_mfma_f32_16x16x32_bf16 v[116:119], v[180:183], v[204:207], v[116:119]
	v_mfma_f32_16x16x32_bf16 v[108:111], v[168:171], v[212:215], v[108:111]
	v_mfma_f32_16x16x32_bf16 v[100:103], v[180:183], v[212:215], v[100:103]
	v_mfma_f32_16x16x32_bf16 v[92:95], v[168:171], v[220:223], v[92:95]
	v_mfma_f32_16x16x32_bf16 v[84:87], v[180:183], v[220:223], v[84:87]
	v_mfma_f32_16x16x32_bf16 v[76:79], v[168:171], v[240:243], v[76:79]
	v_mfma_f32_16x16x32_bf16 v[68:71], v[180:183], v[240:243], v[68:71]
	s_setprio 0
	s_setprio 1
	v_mfma_f32_16x16x32_bf16 v[120:123], v[184:187], v[200:203], 0
	v_mfma_f32_16x16x32_bf16 v[112:115], v[192:195], v[200:203], 0
	v_mfma_f32_16x16x32_bf16 v[104:107], v[184:187], v[208:211], 0
	v_mfma_f32_16x16x32_bf16 v[96:99], v[192:195], v[208:211], 0
	v_mfma_f32_16x16x32_bf16 v[88:91], v[184:187], v[216:219], 0
	v_mfma_f32_16x16x32_bf16 v[80:83], v[192:195], v[216:219], 0
	v_mfma_f32_16x16x32_bf16 v[72:75], v[184:187], v[224:227], 0
	v_mfma_f32_16x16x32_bf16 v[64:67], v[192:195], v[224:227], 0
	v_mfma_f32_16x16x32_bf16 v[120:123], v[188:191], v[204:207], v[120:123]
	v_mfma_f32_16x16x32_bf16 v[112:115], v[196:199], v[204:207], v[112:115]
	v_mfma_f32_16x16x32_bf16 v[104:107], v[188:191], v[212:215], v[104:107]
	v_mfma_f32_16x16x32_bf16 v[96:99], v[196:199], v[212:215], v[96:99]
	v_mfma_f32_16x16x32_bf16 v[88:91], v[188:191], v[220:223], v[88:91]
	v_mfma_f32_16x16x32_bf16 v[80:83], v[196:199], v[220:223], v[80:83]
	v_mfma_f32_16x16x32_bf16 v[72:75], v[188:191], v[240:243], v[72:75]
	v_mfma_f32_16x16x32_bf16 v[64:67], v[196:199], v[240:243], v[64:67]
	s_barrier
	s_setprio 0
	s_add_i32 s90, s82, s3
	v_lshl_add_u64 v[228:229], s[36:37], 0, v[158:159]
	s_mov_b32 m0, s90
	ds_read_b128 v[200:203], v165 offset:16384
	ds_read_b128 v[204:207], v165 offset:17408
	ds_read_b128 v[208:211], v165 offset:18432
	ds_read_b128 v[212:215], v165 offset:19456
	ds_read_b128 v[216:219], v165 offset:20480
	ds_read_b128 v[220:223], v165 offset:21504
	ds_read_b128 v[224:227], v165 offset:22528
	ds_read_b128 v[240:243], v165 offset:23552
	global_load_lds_dwordx4 v[228:229], off
	s_add_i32 m0, s90, 0x2000
	s_add_u32 s90, s36, 0x40000
	v_lshl_add_u64 v[244:245], s[36:37], 0, v[162:163]
	s_addc_u32 s91, s37, 0
	s_add_i32 s93, s83, s3
	global_load_lds_dwordx4 v[244:245], off
	v_lshl_add_u64 v[248:249], s[90:91], 0, v[158:159]
	s_mov_b32 m0, s93
	v_lshl_add_u64 v[250:251], s[38:39], 0, v[160:161]
	global_load_lds_dwordx4 v[248:249], off
	v_lshl_add_u64 v[248:249], s[90:91], 0, v[162:163]
	s_add_i32 m0, s93, 0x2000
	s_nop 0
	global_load_lds_dwordx4 v[248:249], off
	v_lshl_add_u64 v[248:249], s[38:39], 0, v[156:157]
	s_mov_b32 m0, s33
	s_nop 0
	global_load_lds_dwordx4 v[248:249], off
	s_mov_b32 m0, s40
	s_nop 0
	global_load_lds_dwordx4 v[250:251], off
	s_waitcnt vmcnt(8)
	s_waitcnt lgkmcnt(0)
	s_setprio 1
	s_barrier
; #define PG8_STAGE(bufoff, gbase, voff) do { _Pragma("unroll") for (int _i = 0; _i < 2; ++_i) \
;         __builtin_amdgcn_global_load_lds((const unsigned*)((const char*)(gbase) + (voff)[_i]), (PG8_LAS unsigned*)(lds + (bufoff) + ldsw + _i * 8192), 16, 0, 0); } while (0)
; #define PG8_LDA(dst, b, h) do { _Pragma("unroll") for (int m = 0; m < 4; ++m) _Pragma("unroll") for (int k = 0; k < 2; ++k) dst[m][k] = *(const PG8_LAS bf16x8*)(lds + PG8_SA(b, h) + aoff + m * 2048 + k * 1024); } while (0)
; #define PG8_LDB(dst, b, h) do { _Pragma("unroll") for (int n = 0; n < 2; ++n) _Pragma("unroll") for (int k = 0; k < 2; ++k) dst[n][k] = *(const PG8_LAS bf16x8*)(lds + PG8_SB(b, h) + boff + n * 2048 + k * 1024); } while (0)
; #define PG8_MMA(ai, bj, At, Bt) do { __builtin_amdgcn_s_setprio(1); _Pragma("unroll") for (int m = 0; m < 4; ++m) _Pragma("unroll") for (int n = 0; n < 2; ++n) _Pragma("unroll") for (int k = 0; k < 2; ++k) \
;         acc[ai][bj][m][n] = __builtin_amdgcn_mfma_f32_16x16x32_bf16(Bt[n][k], At[m][k], acc[ai][bj][m][n], 0, 0, 0); __builtin_amdgcn_s_setprio(0); } while (0)
; #define PG8_WAIT_V(n) asm volatile("s_waitcnt vmcnt(" #n ")" ::: "memory")
; #define PG8_WAIT_L(n) asm volatile("s_waitcnt lgkmcnt(" #n ")" ::: "memory")
; #define PG8_BAR __builtin_amdgcn_s_barrier()
; #define PG8_SCHED __builtin_amdgcn_sched_barrier(0)
; template <class Epi, class Sched, bool ALIGN_EPI = false, bool SP2 = false>
; __device__ __forceinline__ void gemm_phase(PG8_LAS unsigned char* lds, const Gemm g, const Sched& S, const Epi& E) {
;     ...
;             PG8_WAIT_V(8); PG8_WAIT_L(0); PG8_BAR; PG8_MMA(1, 0, At, B0); PG8_MMA(1, 1, At, B1); PG8_BAR; PG8_SCHED;
;             PG8_LDB(B0, 1, 0); PG8_LDB(B1, 1, 1); PG8_SCHED; PG8_LDA(At, 1, 0); PG8_STAGE(PG8_SA(0, 1), a2 + hstep, voffA);
;             PG8_WAIT_V(8); PG8_WAIT_L(0); PG8_BAR; PG8_MMA(0, 0, At, B0); PG8_MMA(0, 1, At, B1); PG8_BAR; PG8_SCHED;
	v_mfma_f32_16x16x32_bf16 v[60:63], v[136:139], v[200:203], 0
	v_mfma_f32_16x16x32_bf16 v[52:55], v[176:179], v[200:203], 0
	v_mfma_f32_16x16x32_bf16 v[44:47], v[136:139], v[208:211], 0
	v_mfma_f32_16x16x32_bf16 v[36:39], v[176:179], v[208:211], 0
	v_mfma_f32_16x16x32_bf16 v[28:31], v[136:139], v[216:219], 0
	v_mfma_f32_16x16x32_bf16 v[20:23], v[176:179], v[216:219], 0
	v_mfma_f32_16x16x32_bf16 v[12:15], v[136:139], v[224:227], 0
	v_mfma_f32_16x16x32_bf16 v[4:7], v[176:179], v[224:227], 0
	v_mfma_f32_16x16x32_bf16 v[60:63], v[168:171], v[204:207], v[60:63]
	v_mfma_f32_16x16x32_bf16 v[52:55], v[180:183], v[204:207], v[52:55]
	v_mfma_f32_16x16x32_bf16 v[44:47], v[168:171], v[212:215], v[44:47]
	v_mfma_f32_16x16x32_bf16 v[36:39], v[180:183], v[212:215], v[36:39]
	v_mfma_f32_16x16x32_bf16 v[28:31], v[168:171], v[220:223], v[28:31]
	v_mfma_f32_16x16x32_bf16 v[20:23], v[180:183], v[220:223], v[20:23]
	v_mfma_f32_16x16x32_bf16 v[12:15], v[168:171], v[240:243], v[12:15]
	v_mfma_f32_16x16x32_bf16 v[4:7], v[180:183], v[240:243], v[4:7]
	s_setprio 0
	s_setprio 1
	v_mfma_f32_16x16x32_bf16 v[56:59], v[184:187], v[200:203], 0
	v_mfma_f32_16x16x32_bf16 v[48:51], v[192:195], v[200:203], 0
	v_mfma_f32_16x16x32_bf16 v[40:43], v[184:187], v[208:211], 0
	v_mfma_f32_16x16x32_bf16 v[32:35], v[192:195], v[208:211], 0
	v_mfma_f32_16x16x32_bf16 v[24:27], v[184:187], v[216:219], 0
	v_mfma_f32_16x16x32_bf16 v[16:19], v[192:195], v[216:219], 0
	v_mfma_f32_16x16x32_bf16 v[8:11], v[184:187], v[224:227], 0
	v_mfma_f32_16x16x32_bf16 v[0:3], v[192:195], v[224:227], 0
	v_mfma_f32_16x16x32_bf16 v[56:59], v[188:191], v[204:207], v[56:59]
	v_mfma_f32_16x16x32_bf16 v[48:51], v[196:199], v[204:207], v[48:51]
	v_mfma_f32_16x16x32_bf16 v[40:43], v[188:191], v[212:215], v[40:43]
	v_mfma_f32_16x16x32_bf16 v[32:35], v[196:199], v[212:215], v[32:35]
	v_mfma_f32_16x16x32_bf16 v[24:27], v[188:191], v[220:223], v[24:27]
	v_mfma_f32_16x16x32_bf16 v[16:19], v[196:199], v[220:223], v[16:19]
	v_mfma_f32_16x16x32_bf16 v[8:11], v[188:191], v[240:243], v[8:11]
	v_mfma_f32_16x16x32_bf16 v[0:3], v[196:199], v[240:243], v[0:3]
	s_barrier
	s_setprio 0
	s_add_i32 s90, 0, 0x18000
	v_add_u32_e32 v172, s90, v148
	s_add_i32 s91, 0, 0x1c000
	ds_read_b128 v[136:139], v172
	ds_read_b128 v[168:171], v172 offset:1024
	ds_read_b128 v[176:179], v172 offset:2048
	ds_read_b128 v[180:183], v172 offset:3072
	v_add_u32_e32 v172, s91, v148
	ds_read_b128 v[184:187], v172
	ds_read_b128 v[188:191], v172 offset:1024
	ds_read_b128 v[192:195], v172 offset:2048
	ds_read_b128 v[196:199], v172 offset:3072
	s_add_u32 s38, s38, 0x40000
	s_addc_u32 s39, s39, 0
	s_mov_b32 m0, s41
	v_lshl_add_u64 v[252:253], s[38:39], 0, v[156:157]
	ds_read_b128 v[200:203], v165 offset:32768
	ds_read_b128 v[204:207], v165 offset:33792
	ds_read_b128 v[208:211], v165 offset:34816
	ds_read_b128 v[212:215], v165 offset:35840
	ds_read_b128 v[216:219], v165 offset:36864
	ds_read_b128 v[220:223], v165 offset:37888
	ds_read_b128 v[224:227], v165 offset:38912
	ds_read_b128 v[240:243], v165 offset:39936
	global_load_lds_dwordx4 v[252:253], off
	v_lshl_add_u64 v[252:253], s[38:39], 0, v[160:161]
	s_mov_b32 m0, s42
	s_nop 0
	global_load_lds_dwordx4 v[252:253], off
	s_waitcnt vmcnt(8)
	s_waitcnt lgkmcnt(0)
	s_setprio 1
	s_barrier
	v_mfma_f32_16x16x32_bf16 v[124:127], v[136:139], v[200:203], v[124:127]
	v_mfma_f32_16x16x32_bf16 v[116:119], v[176:179], v[200:203], v[116:119]
	v_mfma_f32_16x16x32_bf16 v[108:111], v[136:139], v[208:211], v[108:111]
	v_mfma_f32_16x16x32_bf16 v[100:103], v[176:179], v[208:211], v[100:103]
	v_mfma_f32_16x16x32_bf16 v[92:95], v[136:139], v[216:219], v[92:95]
	v_mfma_f32_16x16x32_bf16 v[84:87], v[176:179], v[216:219], v[84:87]
	v_mfma_f32_16x16x32_bf16 v[76:79], v[136:139], v[224:227], v[76:79]
	v_mfma_f32_16x16x32_bf16 v[68:71], v[176:179], v[224:227], v[68:71]
	v_mfma_f32_16x16x32_bf16 v[124:127], v[168:171], v[204:207], v[124:127]
	v_mfma_f32_16x16x32_bf16 v[116:119], v[180:183], v[204:207], v[116:119]
	v_mfma_f32_16x16x32_bf16 v[108:111], v[168:171], v[212:215], v[108:111]
	v_mfma_f32_16x16x32_bf16 v[100:103], v[180:183], v[212:215], v[100:103]
	v_mfma_f32_16x16x32_bf16 v[92:95], v[168:171], v[220:223], v[92:95]
	v_mfma_f32_16x16x32_bf16 v[84:87], v[180:183], v[220:223], v[84:87]
	v_mfma_f32_16x16x32_bf16 v[76:79], v[168:171], v[240:243], v[76:79]
	v_mfma_f32_16x16x32_bf16 v[68:71], v[180:183], v[240:243], v[68:71]
	s_setprio 0
	s_setprio 1
	v_mfma_f32_16x16x32_bf16 v[120:123], v[184:187], v[200:203], v[120:123]
	v_mfma_f32_16x16x32_bf16 v[112:115], v[192:195], v[200:203], v[112:115]
	v_mfma_f32_16x16x32_bf16 v[104:107], v[184:187], v[208:211], v[104:107]
	v_mfma_f32_16x16x32_bf16 v[96:99], v[192:195], v[208:211], v[96:99]
	v_mfma_f32_16x16x32_bf16 v[88:91], v[184:187], v[216:219], v[88:91]
	v_mfma_f32_16x16x32_bf16 v[80:83], v[192:195], v[216:219], v[80:83]
	v_mfma_f32_16x16x32_bf16 v[72:75], v[184:187], v[224:227], v[72:75]
	v_mfma_f32_16x16x32_bf16 v[64:67], v[192:195], v[224:227], v[64:67]
	v_mfma_f32_16x16x32_bf16 v[120:123], v[188:191], v[204:207], v[120:123]
	v_mfma_f32_16x16x32_bf16 v[112:115], v[196:199], v[204:207], v[112:115]
	v_mfma_f32_16x16x32_bf16 v[104:107], v[188:191], v[212:215], v[104:107]
	v_mfma_f32_16x16x32_bf16 v[96:99], v[196:199], v[212:215], v[96:99]
	v_mfma_f32_16x16x32_bf16 v[88:91], v[188:191], v[220:223], v[88:91]
	v_mfma_f32_16x16x32_bf16 v[80:83], v[196:199], v[220:223], v[80:83]
	v_mfma_f32_16x16x32_bf16 v[72:75], v[188:191], v[240:243], v[72:75]
	v_mfma_f32_16x16x32_bf16 v[64:67], v[196:199], v[240:243], v[64:67]
	s_barrier
; #define PG8_STAGE(bufoff, gbase, voff) do { _Pragma("unroll") for (int _i = 0; _i < 2; ++_i) \
;         __builtin_amdgcn_global_load_lds((const unsigned*)((const char*)(gbase) + (voff)[_i]), (PG8_LAS unsigned*)(lds + (bufoff) + ldsw + _i * 8192), 16, 0, 0); } while (0)
; #define PG8_LDA(dst, b, h) do { _Pragma("unroll") for (int m = 0; m < 4; ++m) _Pragma("unroll") for (int k = 0; k < 2; ++k) dst[m][k] = *(const PG8_LAS bf16x8*)(lds + PG8_SA(b, h) + aoff + m * 2048 + k * 1024); } while (0)
; #define PG8_MMA(ai, bj, At, Bt) do { __builtin_amdgcn_s_setprio(1); _Pragma("unroll") for (int m = 0; m < 4; ++m) _Pragma("unroll") for (int n = 0; n < 2; ++n) _Pragma("unroll") for (int k = 0; k < 2; ++k) \
;         acc[ai][bj][m][n] = __builtin_amdgcn_mfma_f32_16x16x32_bf16(Bt[n][k], At[m][k], acc[ai][bj][m][n], 0, 0, 0); __builtin_amdgcn_s_setprio(0); } while (0)
; #define PG8_WAIT_V(n) asm volatile("s_waitcnt vmcnt(" #n ")" ::: "memory")
; #define PG8_WAIT_L(n) asm volatile("s_waitcnt lgkmcnt(" #n ")" ::: "memory")
; #define PG8_BAR __builtin_amdgcn_s_barrier()
; #define PG8_SCHED __builtin_amdgcn_sched_barrier(0)
; template <class Epi, class Sched, bool ALIGN_EPI = false, bool SP2 = false>
; __device__ __forceinline__ void gemm_phase(PG8_LAS unsigned char* lds, const Gemm g, const Sched& S, const Epi& E) {
;     ...
;         for (int t = 0; t < nt; t += 2) {
;             const bool last = (t == nt - 2);
;     ...
;             PG8_LDA(At, 1, 1); PG8_STAGE(PG8_SB(1, 0), b3, voffB); PG8_STAGE(PG8_SB(1, 1), b3 + hstep, voffB); PG8_STAGE(PG8_SA(1, 0), a3, voffA);
;             PG8_WAIT_V(8); PG8_WAIT_L(0); PG8_BAR; PG8_MMA(1, 0, At, B0); PG8_MMA(1, 1, At, B1); PG8_BAR; PG8_SCHED;
	s_setprio 0
	s_add_i32 s38, s90, s3
	v_lshl_add_u64 v[228:229], v[228:229], 0, s[10:11]
	s_mov_b32 m0, s38
	ds_read_b128 v[200:203], v165 offset:49152
	ds_read_b128 v[204:207], v165 offset:50176
	ds_read_b128 v[208:211], v165 offset:51200
	ds_read_b128 v[212:215], v165 offset:52224
	ds_read_b128 v[216:219], v165 offset:53248
	ds_read_b128 v[220:223], v165 offset:54272
	ds_read_b128 v[224:227], v165 offset:55296
	ds_read_b128 v[240:243], v165 offset:56320
	global_load_lds_dwordx4 v[228:229], off
	s_add_i32 m0, s38, 0x2000
	s_add_u32 s36, s36, 0x40080
	v_lshl_add_u64 v[228:229], v[244:245], 0, s[10:11]
	s_addc_u32 s37, s37, 0
	s_add_i32 s38, s91, s3
	global_load_lds_dwordx4 v[228:229], off
	v_lshl_add_u64 v[228:229], s[36:37], 0, v[158:159]
	s_mov_b32 m0, s38
	s_nop 0
	global_load_lds_dwordx4 v[228:229], off
	v_lshl_add_u64 v[228:229], s[36:37], 0, v[162:163]
	s_add_i32 m0, s38, 0x2000
	s_nop 0
	global_load_lds_dwordx4 v[228:229], off
	v_lshl_add_u64 v[228:229], v[248:249], 0, s[10:11]
	s_mov_b32 m0, s44
	s_nop 0
	global_load_lds_dwordx4 v[228:229], off
	v_lshl_add_u64 v[228:229], v[250:251], 0, s[10:11]
	s_mov_b32 m0, s45
	s_nop 0
	global_load_lds_dwordx4 v[228:229], off
	s_waitcnt vmcnt(8)
	s_waitcnt lgkmcnt(0)
	s_setprio 1
	s_barrier
	v_mfma_f32_16x16x32_bf16 v[60:63], v[136:139], v[200:203], v[60:63]
	v_mfma_f32_16x16x32_bf16 v[52:55], v[176:179], v[200:203], v[52:55]
	v_mfma_f32_16x16x32_bf16 v[44:47], v[136:139], v[208:211], v[44:47]
	v_mfma_f32_16x16x32_bf16 v[36:39], v[176:179], v[208:211], v[36:39]
	v_mfma_f32_16x16x32_bf16 v[28:31], v[136:139], v[216:219], v[28:31]
	v_mfma_f32_16x16x32_bf16 v[20:23], v[176:179], v[216:219], v[20:23]
	v_mfma_f32_16x16x32_bf16 v[12:15], v[136:139], v[224:227], v[12:15]
	v_mfma_f32_16x16x32_bf16 v[4:7], v[176:179], v[224:227], v[4:7]
	v_mfma_f32_16x16x32_bf16 v[60:63], v[168:171], v[204:207], v[60:63]
	v_mfma_f32_16x16x32_bf16 v[52:55], v[180:183], v[204:207], v[52:55]
	v_mfma_f32_16x16x32_bf16 v[44:47], v[168:171], v[212:215], v[44:47]
	v_mfma_f32_16x16x32_bf16 v[36:39], v[180:183], v[212:215], v[36:39]
	v_mfma_f32_16x16x32_bf16 v[28:31], v[168:171], v[220:223], v[28:31]
	v_mfma_f32_16x16x32_bf16 v[20:23], v[180:183], v[220:223], v[20:23]
	v_mfma_f32_16x16x32_bf16 v[12:15], v[168:171], v[240:243], v[12:15]
	v_mfma_f32_16x16x32_bf16 v[4:7], v[180:183], v[240:243], v[4:7]
	s_setprio 0
	s_setprio 1
	v_mfma_f32_16x16x32_bf16 v[56:59], v[184:187], v[200:203], v[56:59]
	v_mfma_f32_16x16x32_bf16 v[48:51], v[192:195], v[200:203], v[48:51]
	v_mfma_f32_16x16x32_bf16 v[40:43], v[184:187], v[208:211], v[40:43]
	v_mfma_f32_16x16x32_bf16 v[32:35], v[192:195], v[208:211], v[32:35]
	v_mfma_f32_16x16x32_bf16 v[24:27], v[184:187], v[216:219], v[24:27]
	v_mfma_f32_16x16x32_bf16 v[16:19], v[192:195], v[216:219], v[16:19]
	v_mfma_f32_16x16x32_bf16 v[8:11], v[184:187], v[224:227], v[8:11]
	v_mfma_f32_16x16x32_bf16 v[0:3], v[192:195], v[224:227], v[0:3]
	v_mfma_f32_16x16x32_bf16 v[56:59], v[188:191], v[204:207], v[56:59]
	v_mfma_f32_16x16x32_bf16 v[48:51], v[196:199], v[204:207], v[48:51]
	v_mfma_f32_16x16x32_bf16 v[40:43], v[188:191], v[212:215], v[40:43]
	v_mfma_f32_16x16x32_bf16 v[32:35], v[196:199], v[212:215], v[32:35]
	v_mfma_f32_16x16x32_bf16 v[24:27], v[188:191], v[220:223], v[24:27]
	v_mfma_f32_16x16x32_bf16 v[16:19], v[196:199], v[220:223], v[16:19]
	v_mfma_f32_16x16x32_bf16 v[8:11], v[188:191], v[240:243], v[8:11]
	v_mfma_f32_16x16x32_bf16 v[0:3], v[196:199], v[240:243], v[0:3]
	s_barrier
	s_setprio 0
	s_add_i32 s89, s89, 2
	s_add_u32 s34, s34, 0x100
	s_addc_u32 s35, s35, 0
	s_add_u32 s87, s87, 0x100
	s_addc_u32 s88, s88, 0
	s_cmp_gt_u32 s89, 13
	s_cbranch_scc1 .Lpeel_done_g0
	.p2align	6

; #define PG8_STAGE(bufoff, gbase, voff) do { _Pragma("unroll") for (int _i = 0; _i < 2; ++_i) \
;         __builtin_amdgcn_global_load_lds((const unsigned*)((const char*)(gbase) + (voff)[_i]), (PG8_LAS unsigned*)(lds + (bufoff) + ldsw + _i * 8192), 16, 0, 0); } while (0)
; #define PG8_LDA(dst, b, h) do { _Pragma("unroll") for (int m = 0; m < 4; ++m) _Pragma("unroll") for (int k = 0; k < 2; ++k) dst[m][k] = *(const PG8_LAS bf16x8*)(lds + PG8_SA(b, h) + aoff + m * 2048 + k * 1024); } while (0)
; #define PG8_LDB(dst, b, h) do { _Pragma("unroll") for (int n = 0; n < 2; ++n) _Pragma("unroll") for (int k = 0; k < 2; ++k) dst[n][k] = *(const PG8_LAS bf16x8*)(lds + PG8_SB(b, h) + boff + n * 2048 + k * 1024); } while (0)
; #define PG8_MMA(ai, bj, At, Bt) do { __builtin_amdgcn_s_setprio(1); _Pragma("unroll") for (int m = 0; m < 4; ++m) _Pragma("unroll") for (int n = 0; n < 2; ++n) _Pragma("unroll") for (int k = 0; k < 2; ++k) \
;         acc[ai][bj][m][n] = __builtin_amdgcn_mfma_f32_16x16x32_bf16(Bt[n][k], At[m][k], acc[ai][bj][m][n], 0, 0, 0); __builtin_amdgcn_s_setprio(0); } while (0)
; #define PG8_BAR __builtin_amdgcn_s_barrier()
; template <class Epi, class Sched, bool ALIGN_EPI = false, bool SP2 = false>
; __device__ __forceinline__ void gemm_phase(PG8_LAS unsigned char* lds, const Gemm g, const Sched& S, const Epi& E) {
;     ...
;         const bool has_next = S.next(ui + 1, nxt);
;         const char* nA = has_next ? (const char*)g.A + (size_t)nxt.pm * tstep : cA; const char* nB = has_next ? (const char*)g.Bt + (size_t)nxt.pn * tstep : cB;
;         for (int t = 0; t < nt; t += 2) {
;             const bool last = (t == nt - 2);
;             const char* a1 = cA + (size_t)(t + 1) * kstep;
;             const char* a2 = last ? nA : cA + (size_t)(t + 2) * kstep; const char* b2 = last ? nB : cB + (size_t)(t + 2) * kstep;
;             const char* a3 = a2 + kstep; const char* b3 = b2 + kstep;
;             if (last && has_next) S.a_ready(nxt);
;             if constexpr (SP2) {
;             PG8_LDB(B0, 0, 0); PG8_LDB(B1, 0, 1); PG8_SCHED; PG8_LDA(At, 0, 0); PG8_STAGE(PG8_SA(1, 1), a1 + hstep, voffA);
;             PG8_WAIT_V(8); PG8_WAIT_L(0); PG8_BAR; PG8_MMA(0, 0, At, B0); PG8_MMA(0, 1, At, B1); PG8_BAR; PG8_SCHED;
;             PG8_LDA(At, 0, 1); PG8_STAGE(PG8_SB(0, 0), b2, voffB); PG8_STAGE(PG8_SB(0, 1), b2 + hstep, voffB); PG8_STAGE(PG8_SA(0, 0), a2, voffA);
.LBB0_371:
	s_add_u32 s20, s20, 0xb0080
	s_addc_u32 s21, s21, 0
	s_add_u32 s46, s24, 0x100
	s_addc_u32 s47, s25, 0
	s_mov_b32 s54, -2
	s_waitcnt lgkmcnt(0)
	ds_read_b128 v[128:131], v161
	ds_read_b128 v[132:135], v161 offset:1024
	ds_read_b128 v[136:139], v161 offset:2048
	ds_read_b128 v[140:143], v161 offset:3072
	ds_read_b128 v[144:147], v163
	ds_read_b128 v[148:151], v163 offset:1024
	ds_read_b128 v[184:187], v163 offset:2048
	ds_read_b128 v[188:191], v163 offset:3072
	s_add_u32 s24, s20, 0xfff50080
	s_addc_u32 s25, s21, -1
	s_cmp_eq_u32 s54, 40
	s_cselect_b32 s27, s1, s25
	s_cselect_b32 s26, s0, s24
	s_cselect_b32 s25, s19, s47
	s_cselect_b32 s24, s18, s46
	v_lshl_add_u64 v[200:201], s[20:21], 0, v[176:177]
	s_add_i32 m0, s29, 0xc000
	ds_read_b128 v[192:195], v202
	ds_read_b128 v[196:199], v202 offset:1024
	ds_read_b128 v[204:207], v202 offset:2048
	ds_read_b128 v[208:211], v202 offset:3072
	ds_read_b128 v[212:215], v202 offset:4096
	ds_read_b128 v[216:219], v202 offset:5120
	ds_read_b128 v[220:223], v202 offset:6144
	ds_read_b128 v[224:227], v202 offset:7168
	global_load_lds_dwordx4 v[200:201], off
	v_lshl_add_u64 v[200:201], s[20:21], 0, v[178:179]
	s_add_i32 m0, s29, 0xe000
	s_nop 0
	global_load_lds_dwordx4 v[200:201], off
	s_waitcnt vmcnt(8)
	s_waitcnt lgkmcnt(0)
	s_setprio 1
	s_barrier
	v_mfma_f32_16x16x32_bf16 v[124:127], v[128:131], v[192:195], 0
	v_mfma_f32_16x16x32_bf16 v[120:123], v[136:139], v[192:195], 0
	v_mfma_f32_16x16x32_bf16 v[108:111], v[128:131], v[204:207], 0
	v_mfma_f32_16x16x32_bf16 v[104:107], v[136:139], v[204:207], 0
	v_mfma_f32_16x16x32_bf16 v[92:95], v[128:131], v[212:215], 0
	v_mfma_f32_16x16x32_bf16 v[88:91], v[136:139], v[212:215], 0
	v_mfma_f32_16x16x32_bf16 v[76:79], v[128:131], v[220:223], 0
	v_mfma_f32_16x16x32_bf16 v[72:75], v[136:139], v[220:223], 0
	v_mfma_f32_16x16x32_bf16 v[124:127], v[132:135], v[196:199], v[124:127]
	v_mfma_f32_16x16x32_bf16 v[120:123], v[140:143], v[196:199], v[120:123]
	v_mfma_f32_16x16x32_bf16 v[108:111], v[132:135], v[208:211], v[108:111]
	v_mfma_f32_16x16x32_bf16 v[104:107], v[140:143], v[208:211], v[104:107]
	v_mfma_f32_16x16x32_bf16 v[92:95], v[132:135], v[216:219], v[92:95]
	v_mfma_f32_16x16x32_bf16 v[88:91], v[140:143], v[216:219], v[88:91]
	v_mfma_f32_16x16x32_bf16 v[76:79], v[132:135], v[224:227], v[76:79]
	v_mfma_f32_16x16x32_bf16 v[72:75], v[140:143], v[224:227], v[72:75]
	s_setprio 0
	s_setprio 1
	v_mfma_f32_16x16x32_bf16 v[116:119], v[144:147], v[192:195], 0
	v_mfma_f32_16x16x32_bf16 v[112:115], v[184:187], v[192:195], 0
	v_mfma_f32_16x16x32_bf16 v[100:103], v[144:147], v[204:207], 0
	v_mfma_f32_16x16x32_bf16 v[96:99], v[184:187], v[204:207], 0
	v_mfma_f32_16x16x32_bf16 v[84:87], v[144:147], v[212:215], 0
	v_mfma_f32_16x16x32_bf16 v[80:83], v[184:187], v[212:215], 0
	v_mfma_f32_16x16x32_bf16 v[68:71], v[144:147], v[220:223], 0
	v_mfma_f32_16x16x32_bf16 v[64:67], v[184:187], v[220:223], 0
	v_mfma_f32_16x16x32_bf16 v[116:119], v[148:151], v[196:199], v[116:119]
	v_mfma_f32_16x16x32_bf16 v[112:115], v[188:191], v[196:199], v[112:115]
	v_mfma_f32_16x16x32_bf16 v[100:103], v[148:151], v[208:211], v[100:103]
	v_mfma_f32_16x16x32_bf16 v[96:99], v[188:191], v[208:211], v[96:99]
	v_mfma_f32_16x16x32_bf16 v[84:87], v[148:151], v[216:219], v[84:87]
	v_mfma_f32_16x16x32_bf16 v[80:83], v[188:191], v[216:219], v[80:83]
	v_mfma_f32_16x16x32_bf16 v[68:71], v[148:151], v[224:227], v[68:71]
	v_mfma_f32_16x16x32_bf16 v[64:67], v[188:191], v[224:227], v[64:67]
	s_barrier
	s_setprio 0
	s_add_i32 s55, s40, s28
	v_lshl_add_u64 v[200:201], s[24:25], 0, v[166:167]
	s_mov_b32 m0, s55
	ds_read_b128 v[192:195], v202 offset:16384
	ds_read_b128 v[196:199], v202 offset:17408
	ds_read_b128 v[204:207], v202 offset:18432
	ds_read_b128 v[208:211], v202 offset:19456
	ds_read_b128 v[212:215], v202 offset:20480
	ds_read_b128 v[216:219], v202 offset:21504
	ds_read_b128 v[220:223], v202 offset:22528
	ds_read_b128 v[224:227], v202 offset:23552
	global_load_lds_dwordx4 v[200:201], off
	s_add_i32 m0, s55, 0x2000
	s_add_u32 s56, s24, 0xb0000
	v_lshl_add_u64 v[228:229], s[24:25], 0, v[170:171]
	s_addc_u32 s57, s25, 0
	s_add_i32 s55, s41, s28
	global_load_lds_dwordx4 v[228:229], off
	v_lshl_add_u64 v[248:249], s[56:57], 0, v[166:167]
	s_mov_b32 m0, s55
	v_lshl_add_u64 v[250:251], s[26:27], 0, v[168:169]
	global_load_lds_dwordx4 v[248:249], off
	v_lshl_add_u64 v[248:249], s[56:57], 0, v[170:171]
	s_add_i32 m0, s55, 0x2000
	s_nop 0
	global_load_lds_dwordx4 v[248:249], off
	v_lshl_add_u64 v[248:249], s[26:27], 0, v[164:165]
	s_mov_b32 m0, s29
	s_nop 0
	global_load_lds_dwordx4 v[248:249], off
	s_mov_b32 m0, s30
	s_nop 0
	global_load_lds_dwordx4 v[250:251], off
	s_waitcnt vmcnt(8)
	s_waitcnt lgkmcnt(0)
	s_setprio 1
	s_barrier
; #define PG8_STAGE(bufoff, gbase, voff) do { _Pragma("unroll") for (int _i = 0; _i < 2; ++_i) \
;         __builtin_amdgcn_global_load_lds((const unsigned*)((const char*)(gbase) + (voff)[_i]), (PG8_LAS unsigned*)(lds + (bufoff) + ldsw + _i * 8192), 16, 0, 0); } while (0)
; #define PG8_LDA(dst, b, h) do { _Pragma("unroll") for (int m = 0; m < 4; ++m) _Pragma("unroll") for (int k = 0; k < 2; ++k) dst[m][k] = *(const PG8_LAS bf16x8*)(lds + PG8_SA(b, h) + aoff + m * 2048 + k * 1024); } while (0)
; #define PG8_LDB(dst, b, h) do { _Pragma("unroll") for (int n = 0; n < 2; ++n) _Pragma("unroll") for (int k = 0; k < 2; ++k) dst[n][k] = *(const PG8_LAS bf16x8*)(lds + PG8_SB(b, h) + boff + n * 2048 + k * 1024); } while (0)
; #define PG8_MMA(ai, bj, At, Bt) do { __builtin_amdgcn_s_setprio(1); _Pragma("unroll") for (int m = 0; m < 4; ++m) _Pragma("unroll") for (int n = 0; n < 2; ++n) _Pragma("unroll") for (int k = 0; k < 2; ++k) \
;         acc[ai][bj][m][n] = __builtin_amdgcn_mfma_f32_16x16x32_bf16(Bt[n][k], At[m][k], acc[ai][bj][m][n], 0, 0, 0); __builtin_amdgcn_s_setprio(0); } while (0)
; #define PG8_WAIT_V(n) asm volatile("s_waitcnt vmcnt(" #n ")" ::: "memory")
; #define PG8_WAIT_L(n) asm volatile("s_waitcnt lgkmcnt(" #n ")" ::: "memory")
; #define PG8_BAR __builtin_amdgcn_s_barrier()
; #define PG8_SCHED __builtin_amdgcn_sched_barrier(0)
; template <class Epi, class Sched, bool ALIGN_EPI = false, bool SP2 = false>
; __device__ __forceinline__ void gemm_phase(PG8_LAS unsigned char* lds, const Gemm g, const Sched& S, const Epi& E) {
;     ...
;             PG8_WAIT_V(8); PG8_WAIT_L(0); PG8_BAR; PG8_MMA(1, 0, At, B0); PG8_MMA(1, 1, At, B1); PG8_BAR; PG8_SCHED;
;             PG8_LDB(B0, 1, 0); PG8_LDB(B1, 1, 1); PG8_SCHED; PG8_LDA(At, 1, 0); PG8_STAGE(PG8_SA(0, 1), a2 + hstep, voffA);
;             PG8_WAIT_V(8); PG8_WAIT_L(0); PG8_BAR; PG8_MMA(0, 0, At, B0); PG8_MMA(0, 1, At, B1); PG8_BAR; PG8_SCHED;
	v_mfma_f32_16x16x32_bf16 v[60:63], v[128:131], v[192:195], 0
	v_mfma_f32_16x16x32_bf16 v[56:59], v[136:139], v[192:195], 0
	v_mfma_f32_16x16x32_bf16 v[44:47], v[128:131], v[204:207], 0
	v_mfma_f32_16x16x32_bf16 v[40:43], v[136:139], v[204:207], 0
	v_mfma_f32_16x16x32_bf16 v[28:31], v[128:131], v[212:215], 0
	v_mfma_f32_16x16x32_bf16 v[24:27], v[136:139], v[212:215], 0
	v_mfma_f32_16x16x32_bf16 v[12:15], v[128:131], v[220:223], 0
	v_mfma_f32_16x16x32_bf16 v[8:11], v[136:139], v[220:223], 0
	v_mfma_f32_16x16x32_bf16 v[60:63], v[132:135], v[196:199], v[60:63]
	v_mfma_f32_16x16x32_bf16 v[56:59], v[140:143], v[196:199], v[56:59]
	v_mfma_f32_16x16x32_bf16 v[44:47], v[132:135], v[208:211], v[44:47]
	v_mfma_f32_16x16x32_bf16 v[40:43], v[140:143], v[208:211], v[40:43]
	v_mfma_f32_16x16x32_bf16 v[28:31], v[132:135], v[216:219], v[28:31]
	v_mfma_f32_16x16x32_bf16 v[24:27], v[140:143], v[216:219], v[24:27]
	v_mfma_f32_16x16x32_bf16 v[12:15], v[132:135], v[224:227], v[12:15]
	v_mfma_f32_16x16x32_bf16 v[8:11], v[140:143], v[224:227], v[8:11]
	s_setprio 0
	s_setprio 1
	v_mfma_f32_16x16x32_bf16 v[52:55], v[144:147], v[192:195], 0
	v_mfma_f32_16x16x32_bf16 v[48:51], v[184:187], v[192:195], 0
	v_mfma_f32_16x16x32_bf16 v[36:39], v[144:147], v[204:207], 0
	v_mfma_f32_16x16x32_bf16 v[32:35], v[184:187], v[204:207], 0
	v_mfma_f32_16x16x32_bf16 v[20:23], v[144:147], v[212:215], 0
	v_mfma_f32_16x16x32_bf16 v[16:19], v[184:187], v[212:215], 0
	v_mfma_f32_16x16x32_bf16 v[4:7], v[144:147], v[220:223], 0
	v_mfma_f32_16x16x32_bf16 v[0:3], v[184:187], v[220:223], 0
	v_mfma_f32_16x16x32_bf16 v[52:55], v[148:151], v[196:199], v[52:55]
	v_mfma_f32_16x16x32_bf16 v[48:51], v[188:191], v[196:199], v[48:51]
	v_mfma_f32_16x16x32_bf16 v[36:39], v[148:151], v[208:211], v[36:39]
	v_mfma_f32_16x16x32_bf16 v[32:35], v[188:191], v[208:211], v[32:35]
	v_mfma_f32_16x16x32_bf16 v[20:23], v[148:151], v[216:219], v[20:23]
	v_mfma_f32_16x16x32_bf16 v[16:19], v[188:191], v[216:219], v[16:19]
	v_mfma_f32_16x16x32_bf16 v[4:7], v[148:151], v[224:227], v[4:7]
	v_mfma_f32_16x16x32_bf16 v[0:3], v[188:191], v[224:227], v[0:3]
	s_barrier
	s_setprio 0
	s_add_i32 s55, 0, 0x18000
	s_add_i32 s56, 0, 0x1c000
	v_add_u32_e32 v140, s55, v159
	v_add_u32_e32 v188, s56, v159
	ds_read_b128 v[128:131], v140
	ds_read_b128 v[132:135], v140 offset:1024
	ds_read_b128 v[136:139], v140 offset:2048
	ds_read_b128 v[140:143], v140 offset:3072
	ds_read_b128 v[144:147], v188
	ds_read_b128 v[148:151], v188 offset:1024
	ds_read_b128 v[184:187], v188 offset:2048
	ds_read_b128 v[188:191], v188 offset:3072
	s_add_u32 s26, s26, 0xb0000
	s_addc_u32 s27, s27, 0
	s_mov_b32 m0, s31
	v_lshl_add_u64 v[252:253], s[26:27], 0, v[164:165]
	ds_read_b128 v[192:195], v202 offset:32768
	ds_read_b128 v[196:199], v202 offset:33792
	ds_read_b128 v[204:207], v202 offset:34816
	ds_read_b128 v[208:211], v202 offset:35840
	ds_read_b128 v[212:215], v202 offset:36864
	ds_read_b128 v[216:219], v202 offset:37888
	ds_read_b128 v[220:223], v202 offset:38912
	ds_read_b128 v[224:227], v202 offset:39936
	global_load_lds_dwordx4 v[252:253], off
	v_lshl_add_u64 v[252:253], s[26:27], 0, v[168:169]
	s_mov_b32 m0, s33
	s_nop 0
	global_load_lds_dwordx4 v[252:253], off
	s_waitcnt vmcnt(8)
	s_waitcnt lgkmcnt(0)
	s_setprio 1
	s_barrier
	v_mfma_f32_16x16x32_bf16 v[124:127], v[128:131], v[192:195], v[124:127]
	v_mfma_f32_16x16x32_bf16 v[120:123], v[136:139], v[192:195], v[120:123]
	v_mfma_f32_16x16x32_bf16 v[108:111], v[128:131], v[204:207], v[108:111]
	v_mfma_f32_16x16x32_bf16 v[104:107], v[136:139], v[204:207], v[104:107]
	v_mfma_f32_16x16x32_bf16 v[92:95], v[128:131], v[212:215], v[92:95]
	v_mfma_f32_16x16x32_bf16 v[88:91], v[136:139], v[212:215], v[88:91]
	v_mfma_f32_16x16x32_bf16 v[76:79], v[128:131], v[220:223], v[76:79]
	v_mfma_f32_16x16x32_bf16 v[72:75], v[136:139], v[220:223], v[72:75]
	v_mfma_f32_16x16x32_bf16 v[124:127], v[132:135], v[196:199], v[124:127]
	v_mfma_f32_16x16x32_bf16 v[120:123], v[140:143], v[196:199], v[120:123]
	v_mfma_f32_16x16x32_bf16 v[108:111], v[132:135], v[208:211], v[108:111]
	v_mfma_f32_16x16x32_bf16 v[104:107], v[140:143], v[208:211], v[104:107]
	v_mfma_f32_16x16x32_bf16 v[92:95], v[132:135], v[216:219], v[92:95]
	v_mfma_f32_16x16x32_bf16 v[88:91], v[140:143], v[216:219], v[88:91]
	v_mfma_f32_16x16x32_bf16 v[76:79], v[132:135], v[224:227], v[76:79]
	v_mfma_f32_16x16x32_bf16 v[72:75], v[140:143], v[224:227], v[72:75]
	s_setprio 0
	s_setprio 1
	v_mfma_f32_16x16x32_bf16 v[116:119], v[144:147], v[192:195], v[116:119]
	v_mfma_f32_16x16x32_bf16 v[112:115], v[184:187], v[192:195], v[112:115]
	v_mfma_f32_16x16x32_bf16 v[100:103], v[144:147], v[204:207], v[100:103]
	v_mfma_f32_16x16x32_bf16 v[96:99], v[184:187], v[204:207], v[96:99]
	v_mfma_f32_16x16x32_bf16 v[84:87], v[144:147], v[212:215], v[84:87]
	v_mfma_f32_16x16x32_bf16 v[80:83], v[184:187], v[212:215], v[80:83]
	v_mfma_f32_16x16x32_bf16 v[68:71], v[144:147], v[220:223], v[68:71]
	v_mfma_f32_16x16x32_bf16 v[64:67], v[184:187], v[220:223], v[64:67]
	v_mfma_f32_16x16x32_bf16 v[116:119], v[148:151], v[196:199], v[116:119]
	v_mfma_f32_16x16x32_bf16 v[112:115], v[188:191], v[196:199], v[112:115]
	v_mfma_f32_16x16x32_bf16 v[100:103], v[148:151], v[208:211], v[100:103]
	v_mfma_f32_16x16x32_bf16 v[96:99], v[188:191], v[208:211], v[96:99]
	v_mfma_f32_16x16x32_bf16 v[84:87], v[148:151], v[216:219], v[84:87]
	v_mfma_f32_16x16x32_bf16 v[80:83], v[188:191], v[216:219], v[80:83]
	v_mfma_f32_16x16x32_bf16 v[68:71], v[148:151], v[224:227], v[68:71]
	v_mfma_f32_16x16x32_bf16 v[64:67], v[188:191], v[224:227], v[64:67]
	s_barrier
; #define PG8_STAGE(bufoff, gbase, voff) do { _Pragma("unroll") for (int _i = 0; _i < 2; ++_i) \
;         __builtin_amdgcn_global_load_lds((const unsigned*)((const char*)(gbase) + (voff)[_i]), (PG8_LAS unsigned*)(lds + (bufoff) + ldsw + _i * 8192), 16, 0, 0); } while (0)
; #define PG8_LDA(dst, b, h) do { _Pragma("unroll") for (int m = 0; m < 4; ++m) _Pragma("unroll") for (int k = 0; k < 2; ++k) dst[m][k] = *(const PG8_LAS bf16x8*)(lds + PG8_SA(b, h) + aoff + m * 2048 + k * 1024); } while (0)
; #define PG8_MMA(ai, bj, At, Bt) do { __builtin_amdgcn_s_setprio(1); _Pragma("unroll") for (int m = 0; m < 4; ++m) _Pragma("unroll") for (int n = 0; n < 2; ++n) _Pragma("unroll") for (int k = 0; k < 2; ++k) \
;         acc[ai][bj][m][n] = __builtin_amdgcn_mfma_f32_16x16x32_bf16(Bt[n][k], At[m][k], acc[ai][bj][m][n], 0, 0, 0); __builtin_amdgcn_s_setprio(0); } while (0)
; #define PG8_WAIT_V(n) asm volatile("s_waitcnt vmcnt(" #n ")" ::: "memory")
; #define PG8_WAIT_L(n) asm volatile("s_waitcnt lgkmcnt(" #n ")" ::: "memory")
; #define PG8_BAR __builtin_amdgcn_s_barrier()
; #define PG8_SCHED __builtin_amdgcn_sched_barrier(0)
; template <class Epi, class Sched, bool ALIGN_EPI = false, bool SP2 = false>
; __device__ __forceinline__ void gemm_phase(PG8_LAS unsigned char* lds, const Gemm g, const Sched& S, const Epi& E) {
;     ...
;         for (int t = 0; t < nt; t += 2) {
;             const bool last = (t == nt - 2);
;     ...
;             PG8_LDA(At, 1, 1); PG8_STAGE(PG8_SB(1, 0), b3, voffB); PG8_STAGE(PG8_SB(1, 1), b3 + hstep, voffB); PG8_STAGE(PG8_SA(1, 0), a3, voffA);
;             PG8_WAIT_V(8); PG8_WAIT_L(0); PG8_BAR; PG8_MMA(1, 0, At, B0); PG8_MMA(1, 1, At, B1); PG8_BAR; PG8_SCHED;
	s_setprio 0
	s_add_i32 s26, s55, s28
	v_lshl_add_u64 v[200:201], v[200:201], 0, s[12:13]
	s_mov_b32 m0, s26
	ds_read_b128 v[192:195], v202 offset:49152
	ds_read_b128 v[196:199], v202 offset:50176
	ds_read_b128 v[204:207], v202 offset:51200
	ds_read_b128 v[208:211], v202 offset:52224
	ds_read_b128 v[212:215], v202 offset:53248
	ds_read_b128 v[216:219], v202 offset:54272
	ds_read_b128 v[220:223], v202 offset:55296
	ds_read_b128 v[224:227], v202 offset:56320
	global_load_lds_dwordx4 v[200:201], off
	s_add_i32 m0, s26, 0x2000
	s_add_u32 s24, s24, 0xb0080
	v_lshl_add_u64 v[200:201], v[228:229], 0, s[12:13]
	s_addc_u32 s25, s25, 0
	s_add_i32 s26, s56, s28
	global_load_lds_dwordx4 v[200:201], off
	v_lshl_add_u64 v[200:201], s[24:25], 0, v[166:167]
	s_mov_b32 m0, s26
	s_nop 0
	global_load_lds_dwordx4 v[200:201], off
	v_lshl_add_u64 v[200:201], s[24:25], 0, v[170:171]
	s_add_i32 m0, s26, 0x2000
	s_nop 0
	global_load_lds_dwordx4 v[200:201], off
	v_lshl_add_u64 v[200:201], v[248:249], 0, s[12:13]
	s_mov_b32 m0, s35
	s_nop 0
	global_load_lds_dwordx4 v[200:201], off
	v_lshl_add_u64 v[200:201], v[250:251], 0, s[12:13]
	s_mov_b32 m0, s36
	s_nop 0
	global_load_lds_dwordx4 v[200:201], off
	s_waitcnt vmcnt(8)
	s_waitcnt lgkmcnt(0)
	s_setprio 1
	s_barrier
	v_mfma_f32_16x16x32_bf16 v[60:63], v[128:131], v[192:195], v[60:63]
	v_mfma_f32_16x16x32_bf16 v[56:59], v[136:139], v[192:195], v[56:59]
	v_mfma_f32_16x16x32_bf16 v[44:47], v[128:131], v[204:207], v[44:47]
	v_mfma_f32_16x16x32_bf16 v[40:43], v[136:139], v[204:207], v[40:43]
	v_mfma_f32_16x16x32_bf16 v[28:31], v[128:131], v[212:215], v[28:31]
	v_mfma_f32_16x16x32_bf16 v[24:27], v[136:139], v[212:215], v[24:27]
	v_mfma_f32_16x16x32_bf16 v[12:15], v[128:131], v[220:223], v[12:15]
	v_mfma_f32_16x16x32_bf16 v[8:11], v[136:139], v[220:223], v[8:11]
	v_mfma_f32_16x16x32_bf16 v[60:63], v[132:135], v[196:199], v[60:63]
	v_mfma_f32_16x16x32_bf16 v[56:59], v[140:143], v[196:199], v[56:59]
	v_mfma_f32_16x16x32_bf16 v[44:47], v[132:135], v[208:211], v[44:47]
	v_mfma_f32_16x16x32_bf16 v[40:43], v[140:143], v[208:211], v[40:43]
	v_mfma_f32_16x16x32_bf16 v[28:31], v[132:135], v[216:219], v[28:31]
	v_mfma_f32_16x16x32_bf16 v[24:27], v[140:143], v[216:219], v[24:27]
	v_mfma_f32_16x16x32_bf16 v[12:15], v[132:135], v[224:227], v[12:15]
	v_mfma_f32_16x16x32_bf16 v[8:11], v[140:143], v[224:227], v[8:11]
	s_setprio 0
	s_setprio 1
	v_mfma_f32_16x16x32_bf16 v[52:55], v[144:147], v[192:195], v[52:55]
	v_mfma_f32_16x16x32_bf16 v[48:51], v[184:187], v[192:195], v[48:51]
	v_mfma_f32_16x16x32_bf16 v[36:39], v[144:147], v[204:207], v[36:39]
	v_mfma_f32_16x16x32_bf16 v[32:35], v[184:187], v[204:207], v[32:35]
	v_mfma_f32_16x16x32_bf16 v[20:23], v[144:147], v[212:215], v[20:23]
	v_mfma_f32_16x16x32_bf16 v[16:19], v[184:187], v[212:215], v[16:19]
	v_mfma_f32_16x16x32_bf16 v[4:7], v[144:147], v[220:223], v[4:7]
	v_mfma_f32_16x16x32_bf16 v[0:3], v[184:187], v[220:223], v[0:3]
	v_mfma_f32_16x16x32_bf16 v[52:55], v[148:151], v[196:199], v[52:55]
	v_mfma_f32_16x16x32_bf16 v[48:51], v[188:191], v[196:199], v[48:51]
	v_mfma_f32_16x16x32_bf16 v[36:39], v[148:151], v[208:211], v[36:39]
	v_mfma_f32_16x16x32_bf16 v[32:35], v[188:191], v[208:211], v[32:35]
	v_mfma_f32_16x16x32_bf16 v[20:23], v[148:151], v[216:219], v[20:23]
	v_mfma_f32_16x16x32_bf16 v[16:19], v[188:191], v[216:219], v[16:19]
	v_mfma_f32_16x16x32_bf16 v[4:7], v[148:151], v[224:227], v[4:7]
	v_mfma_f32_16x16x32_bf16 v[0:3], v[188:191], v[224:227], v[0:3]
	s_barrier
	s_setprio 0
	s_add_i32 s54, s54, 2
	s_add_u32 s20, s20, 0x100
	s_addc_u32 s21, s21, 0
	s_add_u32 s46, s46, 0x100
	s_addc_u32 s47, s47, 0
	s_cmp_gt_u32 s54, 41
	s_cbranch_scc1 .Lpeel_done_g1
	.p2align	6

; #define PG8_STAGE(bufoff, gbase, voff) do { _Pragma("unroll") for (int _i = 0; _i < 2; ++_i) \
;         __builtin_amdgcn_global_load_lds((const unsigned*)((const char*)(gbase) + (voff)[_i]), (PG8_LAS unsigned*)(lds + (bufoff) + ldsw + _i * 8192), 16, 0, 0); } while (0)
; #define PG8_LDA(dst, b, h) do { _Pragma("unroll") for (int m = 0; m < 4; ++m) _Pragma("unroll") for (int k = 0; k < 2; ++k) dst[m][k] = *(const PG8_LAS bf16x8*)(lds + PG8_SA(b, h) + aoff + m * 2048 + k * 1024); } while (0)
; #define PG8_LDB(dst, b, h) do { _Pragma("unroll") for (int n = 0; n < 2; ++n) _Pragma("unroll") for (int k = 0; k < 2; ++k) dst[n][k] = *(const PG8_LAS bf16x8*)(lds + PG8_SB(b, h) + boff + n * 2048 + k * 1024); } while (0)
; #define PG8_MMA(ai, bj, At, Bt) do { __builtin_amdgcn_s_setprio(1); _Pragma("unroll") for (int m = 0; m < 4; ++m) _Pragma("unroll") for (int n = 0; n < 2; ++n) _Pragma("unroll") for (int k = 0; k < 2; ++k) \
;         acc[ai][bj][m][n] = __builtin_amdgcn_mfma_f32_16x16x32_bf16(Bt[n][k], At[m][k], acc[ai][bj][m][n], 0, 0, 0); __builtin_amdgcn_s_setprio(0); } while (0)
; #define PG8_BAR __builtin_amdgcn_s_barrier()
; template <class Epi, class Sched, bool ALIGN_EPI = false, bool SP2 = false>
; __device__ __forceinline__ void gemm_phase(PG8_LAS unsigned char* lds, const Gemm g, const Sched& S, const Epi& E) {
;     ...
;         const bool has_next = S.next(ui + 1, nxt);
;         const char* nA = has_next ? (const char*)g.A + (size_t)nxt.pm * tstep : cA; const char* nB = has_next ? (const char*)g.Bt + (size_t)nxt.pn * tstep : cB;
;         for (int t = 0; t < nt; t += 2) {
;             const bool last = (t == nt - 2);
;             const char* a1 = cA + (size_t)(t + 1) * kstep;
;             const char* a2 = last ? nA : cA + (size_t)(t + 2) * kstep; const char* b2 = last ? nB : cB + (size_t)(t + 2) * kstep;
;             const char* a3 = a2 + kstep; const char* b3 = b2 + kstep;
;             if (last && has_next) S.a_ready(nxt);
;             if constexpr (SP2) {
;             PG8_LDB(B0, 0, 0); PG8_LDB(B1, 0, 1); PG8_SCHED; PG8_LDA(At, 0, 0); PG8_STAGE(PG8_SA(1, 1), a1 + hstep, voffA);
;             PG8_WAIT_V(8); PG8_WAIT_L(0); PG8_BAR; PG8_MMA(0, 0, At, B0); PG8_MMA(0, 1, At, B1); PG8_BAR; PG8_SCHED;
;             PG8_LDA(At, 0, 1); PG8_STAGE(PG8_SB(0, 0), b2, voffB); PG8_STAGE(PG8_SB(0, 1), b2 + hstep, voffB); PG8_STAGE(PG8_SA(0, 0), a2, voffA);
.LBB0_463:
	s_ashr_i32 s21, s20, 31
	s_lshl_b64 s[24:25], s[20:21], 19
	s_add_u32 s24, s76, s24
	s_addc_u32 s25, s77, s25
	s_and_b64 s[26:27], s[10:11], exec
	s_cselect_b32 s13, s25, s1
	s_cselect_b32 s21, s24, s0
	s_ashr_i32 s19, s18, 31
	s_lshl_b64 s[26:27], s[18:19], 19
	s_add_u32 s26, s33, s26
	s_addc_u32 s27, s36, s27
	s_and_b64 s[34:35], s[10:11], exec
	s_cselect_b32 s19, s27, s31
	s_cselect_b32 s58, s26, s30
	s_add_u32 s0, s0, 0x40080
	s_addc_u32 s1, s1, 0
	s_add_u32 s59, s30, 0x100
	s_addc_u32 s80, s31, 0
	s_mov_b32 s81, -2
	ds_read_b128 v[128:131], v149
	ds_read_b128 v[132:135], v149 offset:1024
	ds_read_b128 v[140:143], v149 offset:2048
	ds_read_b128 v[176:179], v149 offset:3072
	ds_read_b128 v[180:183], v150
	ds_read_b128 v[184:187], v150 offset:1024
	ds_read_b128 v[188:191], v150 offset:2048
	ds_read_b128 v[192:195], v150 offset:3072
	s_add_u32 s30, s0, 0xfffc0080
	s_addc_u32 s31, s1, -1
	s_cmp_eq_u32 s81, 12
	s_cselect_b32 s35, s13, s31
	s_cselect_b32 s34, s21, s30
	s_cselect_b32 s31, s19, s80
	s_cselect_b32 s30, s58, s59
	v_lshl_add_u64 v[228:229], s[0:1], 0, v[136:137]
	s_add_i32 m0, s29, 0xc000
	ds_read_b128 v[196:199], v151
	ds_read_b128 v[200:203], v151 offset:1024
	ds_read_b128 v[204:207], v151 offset:2048
	ds_read_b128 v[208:211], v151 offset:3072
	ds_read_b128 v[212:215], v151 offset:4096
	ds_read_b128 v[216:219], v151 offset:5120
	ds_read_b128 v[220:223], v151 offset:6144
	ds_read_b128 v[224:227], v151 offset:7168
	global_load_lds_dwordx4 v[228:229], off
	v_lshl_add_u64 v[228:229], s[0:1], 0, v[138:139]
	s_add_i32 m0, s29, 0xe000
	s_nop 0
	global_load_lds_dwordx4 v[228:229], off
	s_waitcnt vmcnt(8)
	s_waitcnt lgkmcnt(0)
	s_setprio 1
	s_barrier
	v_mfma_f32_16x16x32_bf16 v[124:127], v[128:131], v[196:199], 0
	v_mfma_f32_16x16x32_bf16 v[120:123], v[140:143], v[196:199], 0
	v_mfma_f32_16x16x32_bf16 v[108:111], v[128:131], v[204:207], 0
	v_mfma_f32_16x16x32_bf16 v[104:107], v[140:143], v[204:207], 0
	v_mfma_f32_16x16x32_bf16 v[92:95], v[128:131], v[212:215], 0
	v_mfma_f32_16x16x32_bf16 v[88:91], v[140:143], v[212:215], 0
	v_mfma_f32_16x16x32_bf16 v[76:79], v[128:131], v[220:223], 0
	v_mfma_f32_16x16x32_bf16 v[72:75], v[140:143], v[220:223], 0
	v_mfma_f32_16x16x32_bf16 v[124:127], v[132:135], v[200:203], v[124:127]
	v_mfma_f32_16x16x32_bf16 v[120:123], v[176:179], v[200:203], v[120:123]
	v_mfma_f32_16x16x32_bf16 v[108:111], v[132:135], v[208:211], v[108:111]
	v_mfma_f32_16x16x32_bf16 v[104:107], v[176:179], v[208:211], v[104:107]
	v_mfma_f32_16x16x32_bf16 v[92:95], v[132:135], v[216:219], v[92:95]
	v_mfma_f32_16x16x32_bf16 v[88:91], v[176:179], v[216:219], v[88:91]
	v_mfma_f32_16x16x32_bf16 v[76:79], v[132:135], v[224:227], v[76:79]
	v_mfma_f32_16x16x32_bf16 v[72:75], v[176:179], v[224:227], v[72:75]
	s_setprio 0
	s_setprio 1
	v_mfma_f32_16x16x32_bf16 v[116:119], v[180:183], v[196:199], 0
	v_mfma_f32_16x16x32_bf16 v[112:115], v[188:191], v[196:199], 0
	v_mfma_f32_16x16x32_bf16 v[100:103], v[180:183], v[204:207], 0
	v_mfma_f32_16x16x32_bf16 v[96:99], v[188:191], v[204:207], 0
	v_mfma_f32_16x16x32_bf16 v[84:87], v[180:183], v[212:215], 0
	v_mfma_f32_16x16x32_bf16 v[80:83], v[188:191], v[212:215], 0
	v_mfma_f32_16x16x32_bf16 v[68:71], v[180:183], v[220:223], 0
	v_mfma_f32_16x16x32_bf16 v[64:67], v[188:191], v[220:223], 0
	v_mfma_f32_16x16x32_bf16 v[116:119], v[184:187], v[200:203], v[116:119]
	v_mfma_f32_16x16x32_bf16 v[112:115], v[192:195], v[200:203], v[112:115]
	v_mfma_f32_16x16x32_bf16 v[100:103], v[184:187], v[208:211], v[100:103]
	v_mfma_f32_16x16x32_bf16 v[96:99], v[192:195], v[208:211], v[96:99]
	v_mfma_f32_16x16x32_bf16 v[84:87], v[184:187], v[216:219], v[84:87]
	v_mfma_f32_16x16x32_bf16 v[80:83], v[192:195], v[216:219], v[80:83]
	v_mfma_f32_16x16x32_bf16 v[68:71], v[184:187], v[224:227], v[68:71]
	v_mfma_f32_16x16x32_bf16 v[64:67], v[192:195], v[224:227], v[64:67]
	s_barrier
	s_setprio 0
	s_add_i32 s82, s46, s3
	v_lshl_add_u64 v[228:229], s[30:31], 0, v[158:159]
	s_mov_b32 m0, s82
	ds_read_b128 v[196:199], v151 offset:16384
	ds_read_b128 v[200:203], v151 offset:17408
	ds_read_b128 v[204:207], v151 offset:18432
	ds_read_b128 v[208:211], v151 offset:19456
	ds_read_b128 v[212:215], v151 offset:20480
	ds_read_b128 v[216:219], v151 offset:21504
	ds_read_b128 v[220:223], v151 offset:22528
	ds_read_b128 v[224:227], v151 offset:23552
	global_load_lds_dwordx4 v[228:229], off
	s_add_i32 m0, s82, 0x2000
	s_add_u32 s82, s30, 0x40000
	v_lshl_add_u64 v[248:249], s[30:31], 0, v[162:163]
	s_addc_u32 s83, s31, 0
	s_add_i32 s84, s47, s3
	global_load_lds_dwordx4 v[248:249], off
	v_lshl_add_u64 v[250:251], s[82:83], 0, v[158:159]
	s_mov_b32 m0, s84
	v_lshl_add_u64 v[252:253], s[34:35], 0, v[160:161]
	global_load_lds_dwordx4 v[250:251], off
	v_lshl_add_u64 v[250:251], s[82:83], 0, v[162:163]
	s_add_i32 m0, s84, 0x2000
	s_nop 0
	global_load_lds_dwordx4 v[250:251], off
	v_lshl_add_u64 v[250:251], s[34:35], 0, v[156:157]
	s_mov_b32 m0, s29
	s_nop 0
	global_load_lds_dwordx4 v[250:251], off
	s_mov_b32 m0, s37
	s_nop 0
	global_load_lds_dwordx4 v[252:253], off
	s_waitcnt vmcnt(8)
	s_waitcnt lgkmcnt(0)
	s_setprio 1
	s_barrier
; #define PG8_STAGE(bufoff, gbase, voff) do { _Pragma("unroll") for (int _i = 0; _i < 2; ++_i) \
;         __builtin_amdgcn_global_load_lds((const unsigned*)((const char*)(gbase) + (voff)[_i]), (PG8_LAS unsigned*)(lds + (bufoff) + ldsw + _i * 8192), 16, 0, 0); } while (0)
; #define PG8_LDA(dst, b, h) do { _Pragma("unroll") for (int m = 0; m < 4; ++m) _Pragma("unroll") for (int k = 0; k < 2; ++k) dst[m][k] = *(const PG8_LAS bf16x8*)(lds + PG8_SA(b, h) + aoff + m * 2048 + k * 1024); } while (0)
; #define PG8_LDB(dst, b, h) do { _Pragma("unroll") for (int n = 0; n < 2; ++n) _Pragma("unroll") for (int k = 0; k < 2; ++k) dst[n][k] = *(const PG8_LAS bf16x8*)(lds + PG8_SB(b, h) + boff + n * 2048 + k * 1024); } while (0)
; #define PG8_MMA(ai, bj, At, Bt) do { __builtin_amdgcn_s_setprio(1); _Pragma("unroll") for (int m = 0; m < 4; ++m) _Pragma("unroll") for (int n = 0; n < 2; ++n) _Pragma("unroll") for (int k = 0; k < 2; ++k) \
;         acc[ai][bj][m][n] = __builtin_amdgcn_mfma_f32_16x16x32_bf16(Bt[n][k], At[m][k], acc[ai][bj][m][n], 0, 0, 0); __builtin_amdgcn_s_setprio(0); } while (0)
; #define PG8_WAIT_V(n) asm volatile("s_waitcnt vmcnt(" #n ")" ::: "memory")
; #define PG8_WAIT_L(n) asm volatile("s_waitcnt lgkmcnt(" #n ")" ::: "memory")
; #define PG8_BAR __builtin_amdgcn_s_barrier()
; #define PG8_SCHED __builtin_amdgcn_sched_barrier(0)
; template <class Epi, class Sched, bool ALIGN_EPI = false, bool SP2 = false>
; __device__ __forceinline__ void gemm_phase(PG8_LAS unsigned char* lds, const Gemm g, const Sched& S, const Epi& E) {
;     ...
;             PG8_WAIT_V(8); PG8_WAIT_L(0); PG8_BAR; PG8_MMA(1, 0, At, B0); PG8_MMA(1, 1, At, B1); PG8_BAR; PG8_SCHED;
;             PG8_LDB(B0, 1, 0); PG8_LDB(B1, 1, 1); PG8_SCHED; PG8_LDA(At, 1, 0); PG8_STAGE(PG8_SA(0, 1), a2 + hstep, voffA);
;             PG8_WAIT_V(8); PG8_WAIT_L(0); PG8_BAR; PG8_MMA(0, 0, At, B0); PG8_MMA(0, 1, At, B1); PG8_BAR; PG8_SCHED;
	v_mfma_f32_16x16x32_bf16 v[60:63], v[128:131], v[196:199], 0
	v_mfma_f32_16x16x32_bf16 v[56:59], v[140:143], v[196:199], 0
	v_mfma_f32_16x16x32_bf16 v[44:47], v[128:131], v[204:207], 0
	v_mfma_f32_16x16x32_bf16 v[40:43], v[140:143], v[204:207], 0
	v_mfma_f32_16x16x32_bf16 v[28:31], v[128:131], v[212:215], 0
	v_mfma_f32_16x16x32_bf16 v[24:27], v[140:143], v[212:215], 0
	v_mfma_f32_16x16x32_bf16 v[12:15], v[128:131], v[220:223], 0
	v_mfma_f32_16x16x32_bf16 v[8:11], v[140:143], v[220:223], 0
	v_mfma_f32_16x16x32_bf16 v[60:63], v[132:135], v[200:203], v[60:63]
	v_mfma_f32_16x16x32_bf16 v[56:59], v[176:179], v[200:203], v[56:59]
	v_mfma_f32_16x16x32_bf16 v[44:47], v[132:135], v[208:211], v[44:47]
	v_mfma_f32_16x16x32_bf16 v[40:43], v[176:179], v[208:211], v[40:43]
	v_mfma_f32_16x16x32_bf16 v[28:31], v[132:135], v[216:219], v[28:31]
	v_mfma_f32_16x16x32_bf16 v[24:27], v[176:179], v[216:219], v[24:27]
	v_mfma_f32_16x16x32_bf16 v[12:15], v[132:135], v[224:227], v[12:15]
	v_mfma_f32_16x16x32_bf16 v[8:11], v[176:179], v[224:227], v[8:11]
	s_setprio 0
	s_setprio 1
	v_mfma_f32_16x16x32_bf16 v[52:55], v[180:183], v[196:199], 0
	v_mfma_f32_16x16x32_bf16 v[48:51], v[188:191], v[196:199], 0
	v_mfma_f32_16x16x32_bf16 v[36:39], v[180:183], v[204:207], 0
	v_mfma_f32_16x16x32_bf16 v[32:35], v[188:191], v[204:207], 0
	v_mfma_f32_16x16x32_bf16 v[20:23], v[180:183], v[212:215], 0
	v_mfma_f32_16x16x32_bf16 v[16:19], v[188:191], v[212:215], 0
	v_mfma_f32_16x16x32_bf16 v[4:7], v[180:183], v[220:223], 0
	v_mfma_f32_16x16x32_bf16 v[0:3], v[188:191], v[220:223], 0
	v_mfma_f32_16x16x32_bf16 v[52:55], v[184:187], v[200:203], v[52:55]
	v_mfma_f32_16x16x32_bf16 v[48:51], v[192:195], v[200:203], v[48:51]
	v_mfma_f32_16x16x32_bf16 v[36:39], v[184:187], v[208:211], v[36:39]
	v_mfma_f32_16x16x32_bf16 v[32:35], v[192:195], v[208:211], v[32:35]
	v_mfma_f32_16x16x32_bf16 v[20:23], v[184:187], v[216:219], v[20:23]
	v_mfma_f32_16x16x32_bf16 v[16:19], v[192:195], v[216:219], v[16:19]
	v_mfma_f32_16x16x32_bf16 v[4:7], v[184:187], v[224:227], v[4:7]
	v_mfma_f32_16x16x32_bf16 v[0:3], v[192:195], v[224:227], v[0:3]
	s_barrier
	s_setprio 0
	s_add_i32 s82, 0, 0x18000
	v_add_u32_e32 v144, s82, v146
	s_add_i32 s83, 0, 0x1c000
	ds_read_b128 v[128:131], v144
	ds_read_b128 v[132:135], v144 offset:1024
	ds_read_b128 v[140:143], v144 offset:2048
	ds_read_b128 v[176:179], v144 offset:3072
	v_add_u32_e32 v144, s83, v146
	ds_read_b128 v[180:183], v144
	ds_read_b128 v[184:187], v144 offset:1024
	ds_read_b128 v[188:191], v144 offset:2048
	ds_read_b128 v[192:195], v144 offset:3072
	s_add_u32 s34, s34, 0x40000
	s_addc_u32 s35, s35, 0
	s_mov_b32 m0, s38
	v_lshl_add_u64 v[238:239], s[34:35], 0, v[156:157]
	ds_read_b128 v[196:199], v151 offset:32768
	ds_read_b128 v[200:203], v151 offset:33792
	ds_read_b128 v[204:207], v151 offset:34816
	ds_read_b128 v[208:211], v151 offset:35840
	ds_read_b128 v[212:215], v151 offset:36864
	ds_read_b128 v[216:219], v151 offset:37888
	ds_read_b128 v[220:223], v151 offset:38912
	ds_read_b128 v[224:227], v151 offset:39936
	global_load_lds_dwordx4 v[238:239], off
	v_lshl_add_u64 v[238:239], s[34:35], 0, v[160:161]
	s_mov_b32 m0, s39
	s_nop 0
	global_load_lds_dwordx4 v[238:239], off
	s_waitcnt vmcnt(8)
	s_waitcnt lgkmcnt(0)
	s_setprio 1
	s_barrier
	v_mfma_f32_16x16x32_bf16 v[124:127], v[128:131], v[196:199], v[124:127]
	v_mfma_f32_16x16x32_bf16 v[120:123], v[140:143], v[196:199], v[120:123]
	v_mfma_f32_16x16x32_bf16 v[108:111], v[128:131], v[204:207], v[108:111]
	v_mfma_f32_16x16x32_bf16 v[104:107], v[140:143], v[204:207], v[104:107]
	v_mfma_f32_16x16x32_bf16 v[92:95], v[128:131], v[212:215], v[92:95]
	v_mfma_f32_16x16x32_bf16 v[88:91], v[140:143], v[212:215], v[88:91]
	v_mfma_f32_16x16x32_bf16 v[76:79], v[128:131], v[220:223], v[76:79]
	v_mfma_f32_16x16x32_bf16 v[72:75], v[140:143], v[220:223], v[72:75]
	v_mfma_f32_16x16x32_bf16 v[124:127], v[132:135], v[200:203], v[124:127]
	v_mfma_f32_16x16x32_bf16 v[120:123], v[176:179], v[200:203], v[120:123]
	v_mfma_f32_16x16x32_bf16 v[108:111], v[132:135], v[208:211], v[108:111]
	v_mfma_f32_16x16x32_bf16 v[104:107], v[176:179], v[208:211], v[104:107]
	v_mfma_f32_16x16x32_bf16 v[92:95], v[132:135], v[216:219], v[92:95]
	v_mfma_f32_16x16x32_bf16 v[88:91], v[176:179], v[216:219], v[88:91]
	v_mfma_f32_16x16x32_bf16 v[76:79], v[132:135], v[224:227], v[76:79]
	v_mfma_f32_16x16x32_bf16 v[72:75], v[176:179], v[224:227], v[72:75]
	s_setprio 0
	s_setprio 1
	v_mfma_f32_16x16x32_bf16 v[116:119], v[180:183], v[196:199], v[116:119]
	v_mfma_f32_16x16x32_bf16 v[112:115], v[188:191], v[196:199], v[112:115]
	v_mfma_f32_16x16x32_bf16 v[100:103], v[180:183], v[204:207], v[100:103]
	v_mfma_f32_16x16x32_bf16 v[96:99], v[188:191], v[204:207], v[96:99]
	v_mfma_f32_16x16x32_bf16 v[84:87], v[180:183], v[212:215], v[84:87]
	v_mfma_f32_16x16x32_bf16 v[80:83], v[188:191], v[212:215], v[80:83]
	v_mfma_f32_16x16x32_bf16 v[68:71], v[180:183], v[220:223], v[68:71]
	v_mfma_f32_16x16x32_bf16 v[64:67], v[188:191], v[220:223], v[64:67]
	v_mfma_f32_16x16x32_bf16 v[116:119], v[184:187], v[200:203], v[116:119]
	v_mfma_f32_16x16x32_bf16 v[112:115], v[192:195], v[200:203], v[112:115]
	v_mfma_f32_16x16x32_bf16 v[100:103], v[184:187], v[208:211], v[100:103]
	v_mfma_f32_16x16x32_bf16 v[96:99], v[192:195], v[208:211], v[96:99]
	v_mfma_f32_16x16x32_bf16 v[84:87], v[184:187], v[216:219], v[84:87]
	v_mfma_f32_16x16x32_bf16 v[80:83], v[192:195], v[216:219], v[80:83]
	v_mfma_f32_16x16x32_bf16 v[68:71], v[184:187], v[224:227], v[68:71]
	v_mfma_f32_16x16x32_bf16 v[64:67], v[192:195], v[224:227], v[64:67]
	s_barrier
; #define PG8_STAGE(bufoff, gbase, voff) do { _Pragma("unroll") for (int _i = 0; _i < 2; ++_i) \
;         __builtin_amdgcn_global_load_lds((const unsigned*)((const char*)(gbase) + (voff)[_i]), (PG8_LAS unsigned*)(lds + (bufoff) + ldsw + _i * 8192), 16, 0, 0); } while (0)
; #define PG8_LDA(dst, b, h) do { _Pragma("unroll") for (int m = 0; m < 4; ++m) _Pragma("unroll") for (int k = 0; k < 2; ++k) dst[m][k] = *(const PG8_LAS bf16x8*)(lds + PG8_SA(b, h) + aoff + m * 2048 + k * 1024); } while (0)
; #define PG8_MMA(ai, bj, At, Bt) do { __builtin_amdgcn_s_setprio(1); _Pragma("unroll") for (int m = 0; m < 4; ++m) _Pragma("unroll") for (int n = 0; n < 2; ++n) _Pragma("unroll") for (int k = 0; k < 2; ++k) \
;         acc[ai][bj][m][n] = __builtin_amdgcn_mfma_f32_16x16x32_bf16(Bt[n][k], At[m][k], acc[ai][bj][m][n], 0, 0, 0); __builtin_amdgcn_s_setprio(0); } while (0)
; #define PG8_WAIT_V(n) asm volatile("s_waitcnt vmcnt(" #n ")" ::: "memory")
; #define PG8_WAIT_L(n) asm volatile("s_waitcnt lgkmcnt(" #n ")" ::: "memory")
; #define PG8_BAR __builtin_amdgcn_s_barrier()
; #define PG8_SCHED __builtin_amdgcn_sched_barrier(0)
; template <class Epi, class Sched, bool ALIGN_EPI = false, bool SP2 = false>
; __device__ __forceinline__ void gemm_phase(PG8_LAS unsigned char* lds, const Gemm g, const Sched& S, const Epi& E) {
;     ...
;         for (int t = 0; t < nt; t += 2) {
;             const bool last = (t == nt - 2);
;     ...
;             PG8_LDA(At, 1, 1); PG8_STAGE(PG8_SB(1, 0), b3, voffB); PG8_STAGE(PG8_SB(1, 1), b3 + hstep, voffB); PG8_STAGE(PG8_SA(1, 0), a3, voffA);
;             PG8_WAIT_V(8); PG8_WAIT_L(0); PG8_BAR; PG8_MMA(1, 0, At, B0); PG8_MMA(1, 1, At, B1); PG8_BAR; PG8_SCHED;
	s_setprio 0
	s_add_i32 s34, s82, s3
	v_lshl_add_u64 v[228:229], v[228:229], 0, s[6:7]
	s_mov_b32 m0, s34
	ds_read_b128 v[196:199], v151 offset:49152
	ds_read_b128 v[200:203], v151 offset:50176
	ds_read_b128 v[204:207], v151 offset:51200
	ds_read_b128 v[208:211], v151 offset:52224
	ds_read_b128 v[212:215], v151 offset:53248
	ds_read_b128 v[216:219], v151 offset:54272
	ds_read_b128 v[220:223], v151 offset:55296
	ds_read_b128 v[224:227], v151 offset:56320
	global_load_lds_dwordx4 v[228:229], off
	s_add_i32 m0, s34, 0x2000
	s_add_u32 s30, s30, 0x40080
	v_lshl_add_u64 v[228:229], v[248:249], 0, s[6:7]
	s_addc_u32 s31, s31, 0
	s_add_i32 s34, s83, s3
	global_load_lds_dwordx4 v[228:229], off
	v_lshl_add_u64 v[228:229], s[30:31], 0, v[158:159]
	s_mov_b32 m0, s34
	s_nop 0
	global_load_lds_dwordx4 v[228:229], off
	v_lshl_add_u64 v[228:229], s[30:31], 0, v[162:163]
	s_add_i32 m0, s34, 0x2000
	s_nop 0
	global_load_lds_dwordx4 v[228:229], off
	v_lshl_add_u64 v[228:229], v[250:251], 0, s[6:7]
	s_mov_b32 m0, s41
	s_nop 0
	global_load_lds_dwordx4 v[228:229], off
	v_lshl_add_u64 v[228:229], v[252:253], 0, s[6:7]
	s_mov_b32 m0, s42
	s_nop 0
	global_load_lds_dwordx4 v[228:229], off
	s_waitcnt vmcnt(8)
	s_waitcnt lgkmcnt(0)
	s_setprio 1
	s_barrier
	v_mfma_f32_16x16x32_bf16 v[60:63], v[128:131], v[196:199], v[60:63]
	v_mfma_f32_16x16x32_bf16 v[56:59], v[140:143], v[196:199], v[56:59]
	v_mfma_f32_16x16x32_bf16 v[44:47], v[128:131], v[204:207], v[44:47]
	v_mfma_f32_16x16x32_bf16 v[40:43], v[140:143], v[204:207], v[40:43]
	v_mfma_f32_16x16x32_bf16 v[28:31], v[128:131], v[212:215], v[28:31]
	v_mfma_f32_16x16x32_bf16 v[24:27], v[140:143], v[212:215], v[24:27]
	v_mfma_f32_16x16x32_bf16 v[12:15], v[128:131], v[220:223], v[12:15]
	v_mfma_f32_16x16x32_bf16 v[8:11], v[140:143], v[220:223], v[8:11]
	v_mfma_f32_16x16x32_bf16 v[60:63], v[132:135], v[200:203], v[60:63]
	v_mfma_f32_16x16x32_bf16 v[56:59], v[176:179], v[200:203], v[56:59]
	v_mfma_f32_16x16x32_bf16 v[44:47], v[132:135], v[208:211], v[44:47]
	v_mfma_f32_16x16x32_bf16 v[40:43], v[176:179], v[208:211], v[40:43]
	v_mfma_f32_16x16x32_bf16 v[28:31], v[132:135], v[216:219], v[28:31]
	v_mfma_f32_16x16x32_bf16 v[24:27], v[176:179], v[216:219], v[24:27]
	v_mfma_f32_16x16x32_bf16 v[12:15], v[132:135], v[224:227], v[12:15]
	v_mfma_f32_16x16x32_bf16 v[8:11], v[176:179], v[224:227], v[8:11]
	s_setprio 0
	s_setprio 1
	v_mfma_f32_16x16x32_bf16 v[52:55], v[180:183], v[196:199], v[52:55]
	v_mfma_f32_16x16x32_bf16 v[48:51], v[188:191], v[196:199], v[48:51]
	v_mfma_f32_16x16x32_bf16 v[36:39], v[180:183], v[204:207], v[36:39]
	v_mfma_f32_16x16x32_bf16 v[32:35], v[188:191], v[204:207], v[32:35]
	v_mfma_f32_16x16x32_bf16 v[20:23], v[180:183], v[212:215], v[20:23]
	v_mfma_f32_16x16x32_bf16 v[16:19], v[188:191], v[212:215], v[16:19]
	v_mfma_f32_16x16x32_bf16 v[4:7], v[180:183], v[220:223], v[4:7]
	v_mfma_f32_16x16x32_bf16 v[0:3], v[188:191], v[220:223], v[0:3]
	v_mfma_f32_16x16x32_bf16 v[52:55], v[184:187], v[200:203], v[52:55]
	v_mfma_f32_16x16x32_bf16 v[48:51], v[192:195], v[200:203], v[48:51]
	v_mfma_f32_16x16x32_bf16 v[36:39], v[184:187], v[208:211], v[36:39]
	v_mfma_f32_16x16x32_bf16 v[32:35], v[192:195], v[208:211], v[32:35]
	v_mfma_f32_16x16x32_bf16 v[20:23], v[184:187], v[216:219], v[20:23]
	v_mfma_f32_16x16x32_bf16 v[16:19], v[192:195], v[216:219], v[16:19]
	v_mfma_f32_16x16x32_bf16 v[4:7], v[184:187], v[224:227], v[4:7]
	v_mfma_f32_16x16x32_bf16 v[0:3], v[192:195], v[224:227], v[0:3]
	s_barrier
	s_setprio 0
	s_add_i32 s81, s81, 2
	s_add_u32 s0, s0, 0x100
	s_addc_u32 s1, s1, 0
	s_add_u32 s59, s59, 0x100
	s_addc_u32 s80, s80, 0
	s_cmp_gt_u32 s81, 13
	s_cbranch_scc1 .Lpeel_done_g2
	.p2align	6

; #define PG8_STAGE(bufoff, gbase, voff) do { _Pragma("unroll") for (int _i = 0; _i < 2; ++_i) \
;         __builtin_amdgcn_global_load_lds((const unsigned*)((const char*)(gbase) + (voff)[_i]), (PG8_LAS unsigned*)(lds + (bufoff) + ldsw + _i * 8192), 16, 0, 0); } while (0)
; #define PG8_LDA(dst, b, h) do { _Pragma("unroll") for (int m = 0; m < 4; ++m) _Pragma("unroll") for (int k = 0; k < 2; ++k) dst[m][k] = *(const PG8_LAS bf16x8*)(lds + PG8_SA(b, h) + aoff + m * 2048 + k * 1024); } while (0)
; #define PG8_LDB(dst, b, h) do { _Pragma("unroll") for (int n = 0; n < 2; ++n) _Pragma("unroll") for (int k = 0; k < 2; ++k) dst[n][k] = *(const PG8_LAS bf16x8*)(lds + PG8_SB(b, h) + boff + n * 2048 + k * 1024); } while (0)
; #define PG8_MMA(ai, bj, At, Bt) do { __builtin_amdgcn_s_setprio(1); _Pragma("unroll") for (int m = 0; m < 4; ++m) _Pragma("unroll") for (int n = 0; n < 2; ++n) _Pragma("unroll") for (int k = 0; k < 2; ++k) \
;         acc[ai][bj][m][n] = __builtin_amdgcn_mfma_f32_16x16x32_bf16(Bt[n][k], At[m][k], acc[ai][bj][m][n], 0, 0, 0); __builtin_amdgcn_s_setprio(0); } while (0)
; #define PG8_BAR __builtin_amdgcn_s_barrier()
; template <class Epi, class Sched, bool ALIGN_EPI = false, bool SP2 = false>
; __device__ __forceinline__ void gemm_phase(PG8_LAS unsigned char* lds, const Gemm g, const Sched& S, const Epi& E) {
;     ...
;         const bool has_next = S.next(ui + 1, nxt);
;         const char* nA = has_next ? (const char*)g.A + (size_t)nxt.pm * tstep : cA; const char* nB = has_next ? (const char*)g.Bt + (size_t)nxt.pn * tstep : cB;
;         for (int t = 0; t < nt; t += 2) {
;             const bool last = (t == nt - 2);
;             const char* a1 = cA + (size_t)(t + 1) * kstep;
;             const char* a2 = last ? nA : cA + (size_t)(t + 2) * kstep; const char* b2 = last ? nB : cB + (size_t)(t + 2) * kstep;
;             const char* a3 = a2 + kstep; const char* b3 = b2 + kstep;
;             if (last && has_next) S.a_ready(nxt);
;             if constexpr (SP2) {
;             PG8_LDB(B0, 0, 0); PG8_LDB(B1, 0, 1); PG8_SCHED; PG8_LDA(At, 0, 0); PG8_STAGE(PG8_SA(1, 1), a1 + hstep, voffA);
;             PG8_WAIT_V(8); PG8_WAIT_L(0); PG8_BAR; PG8_MMA(0, 0, At, B0); PG8_MMA(0, 1, At, B1); PG8_BAR; PG8_SCHED;
;             PG8_LDA(At, 0, 1); PG8_STAGE(PG8_SB(0, 0), b2, voffB); PG8_STAGE(PG8_SB(0, 1), b2 + hstep, voffB); PG8_STAGE(PG8_SA(0, 0), a2, voffA);
.LBB0_1229:
	s_ashr_i32 s19, s18, 31
	s_lshl_b64 s[20:21], s[18:19], 19
	s_add_u32 s20, s48, s20
	s_addc_u32 s21, s49, s21
	s_and_b64 s[22:23], s[10:11], exec
	s_cselect_b32 s19, s21, s27
	s_cselect_b32 s25, s20, s26
	s_ashr_i32 s17, s16, 31
	s_lshl_b64 s[22:23], s[16:17], 19
	s_add_u32 s22, s2, s22
	s_addc_u32 s23, s3, s23
	s_and_b64 s[30:31], s[10:11], exec
	s_cselect_b32 s17, s23, s29
	s_cselect_b32 s47, s22, s28
	s_add_u32 s26, s26, 0x40080
	s_addc_u32 s27, s27, 0
	s_add_u32 s50, s28, 0x100
	s_addc_u32 s51, s29, 0
	s_mov_b32 s52, -2
	s_waitcnt lgkmcnt(0)
	ds_read_b128 v[128:131], v200
	ds_read_b128 v[132:135], v200 offset:1024
	ds_read_b128 v[136:139], v200 offset:2048
	ds_read_b128 v[140:143], v200 offset:3072
	ds_read_b128 v[144:147], v201
	ds_read_b128 v[148:151], v201 offset:1024
	ds_read_b128 v[182:185], v201 offset:2048
	ds_read_b128 v[186:189], v201 offset:3072
	s_add_u32 s28, s26, 0xfffc0080
	s_addc_u32 s29, s27, -1
	s_cmp_eq_u32 s52, 12
	s_cselect_b32 s31, s19, s29
	s_cselect_b32 s30, s25, s28
	s_cselect_b32 s29, s17, s51
	s_cselect_b32 s28, s47, s50
	v_lshl_add_u64 v[198:199], s[26:27], 0, v[174:175]
	s_add_i32 m0, s34, 0xc000
	ds_read_b128 v[190:193], v202
	ds_read_b128 v[194:197], v202 offset:1024
	ds_read_b128 v[204:207], v202 offset:2048
	ds_read_b128 v[208:211], v202 offset:3072
	ds_read_b128 v[212:215], v202 offset:4096
	ds_read_b128 v[216:219], v202 offset:5120
	ds_read_b128 v[220:223], v202 offset:6144
	ds_read_b128 v[224:227], v202 offset:7168
	global_load_lds_dwordx4 v[198:199], off
	v_lshl_add_u64 v[198:199], s[26:27], 0, v[176:177]
	s_add_i32 m0, s34, 0xe000
	s_nop 0
	global_load_lds_dwordx4 v[198:199], off
	s_waitcnt vmcnt(8)
	s_waitcnt lgkmcnt(0)
	s_setprio 1
	s_barrier
	v_mfma_f32_16x16x32_bf16 v[124:127], v[128:131], v[190:193], 0
	v_mfma_f32_16x16x32_bf16 v[120:123], v[136:139], v[190:193], 0
	v_mfma_f32_16x16x32_bf16 v[108:111], v[128:131], v[204:207], 0
	v_mfma_f32_16x16x32_bf16 v[104:107], v[136:139], v[204:207], 0
	v_mfma_f32_16x16x32_bf16 v[92:95], v[128:131], v[212:215], 0
	v_mfma_f32_16x16x32_bf16 v[88:91], v[136:139], v[212:215], 0
	v_mfma_f32_16x16x32_bf16 v[76:79], v[128:131], v[220:223], 0
	v_mfma_f32_16x16x32_bf16 v[72:75], v[136:139], v[220:223], 0
	v_mfma_f32_16x16x32_bf16 v[124:127], v[132:135], v[194:197], v[124:127]
	v_mfma_f32_16x16x32_bf16 v[120:123], v[140:143], v[194:197], v[120:123]
	v_mfma_f32_16x16x32_bf16 v[108:111], v[132:135], v[208:211], v[108:111]
	v_mfma_f32_16x16x32_bf16 v[104:107], v[140:143], v[208:211], v[104:107]
	v_mfma_f32_16x16x32_bf16 v[92:95], v[132:135], v[216:219], v[92:95]
	v_mfma_f32_16x16x32_bf16 v[88:91], v[140:143], v[216:219], v[88:91]
	v_mfma_f32_16x16x32_bf16 v[76:79], v[132:135], v[224:227], v[76:79]
	v_mfma_f32_16x16x32_bf16 v[72:75], v[140:143], v[224:227], v[72:75]
	s_setprio 0
	s_setprio 1
	v_mfma_f32_16x16x32_bf16 v[116:119], v[144:147], v[190:193], 0
	v_mfma_f32_16x16x32_bf16 v[112:115], v[182:185], v[190:193], 0
	v_mfma_f32_16x16x32_bf16 v[100:103], v[144:147], v[204:207], 0
	v_mfma_f32_16x16x32_bf16 v[96:99], v[182:185], v[204:207], 0
	v_mfma_f32_16x16x32_bf16 v[84:87], v[144:147], v[212:215], 0
	v_mfma_f32_16x16x32_bf16 v[80:83], v[182:185], v[212:215], 0
	v_mfma_f32_16x16x32_bf16 v[68:71], v[144:147], v[220:223], 0
	v_mfma_f32_16x16x32_bf16 v[64:67], v[182:185], v[220:223], 0
	v_mfma_f32_16x16x32_bf16 v[116:119], v[148:151], v[194:197], v[116:119]
	v_mfma_f32_16x16x32_bf16 v[112:115], v[186:189], v[194:197], v[112:115]
	v_mfma_f32_16x16x32_bf16 v[100:103], v[148:151], v[208:211], v[100:103]
	v_mfma_f32_16x16x32_bf16 v[96:99], v[186:189], v[208:211], v[96:99]
	v_mfma_f32_16x16x32_bf16 v[84:87], v[148:151], v[216:219], v[84:87]
	v_mfma_f32_16x16x32_bf16 v[80:83], v[186:189], v[216:219], v[80:83]
	v_mfma_f32_16x16x32_bf16 v[68:71], v[148:151], v[224:227], v[68:71]
	v_mfma_f32_16x16x32_bf16 v[64:67], v[186:189], v[224:227], v[64:67]
	s_barrier
	s_setprio 0
	s_add_i32 s53, s44, s33
	v_lshl_add_u64 v[198:199], s[28:29], 0, v[158:159]
	s_mov_b32 m0, s53
	ds_read_b128 v[190:193], v202 offset:16384
	ds_read_b128 v[194:197], v202 offset:17408
	ds_read_b128 v[204:207], v202 offset:18432
	ds_read_b128 v[208:211], v202 offset:19456
	ds_read_b128 v[212:215], v202 offset:20480
	ds_read_b128 v[216:219], v202 offset:21504
	ds_read_b128 v[220:223], v202 offset:22528
	ds_read_b128 v[224:227], v202 offset:23552
	global_load_lds_dwordx4 v[198:199], off
	s_add_i32 m0, s53, 0x2000
	s_add_u32 s54, s28, 0x40000
	v_lshl_add_u64 v[228:229], s[28:29], 0, v[162:163]
	s_addc_u32 s55, s29, 0
	s_add_i32 s53, s45, s33
	global_load_lds_dwordx4 v[228:229], off
	v_lshl_add_u64 v[238:239], s[54:55], 0, v[158:159]
	s_mov_b32 m0, s53
	v_lshl_add_u64 v[246:247], s[30:31], 0, v[160:161]
	global_load_lds_dwordx4 v[238:239], off
	v_lshl_add_u64 v[238:239], s[54:55], 0, v[162:163]
	s_add_i32 m0, s53, 0x2000
	s_nop 0
	global_load_lds_dwordx4 v[238:239], off
	v_lshl_add_u64 v[238:239], s[30:31], 0, v[156:157]
	s_mov_b32 m0, s34
	s_nop 0
	global_load_lds_dwordx4 v[238:239], off
	s_mov_b32 m0, s35
	s_nop 0
	global_load_lds_dwordx4 v[246:247], off
	s_waitcnt vmcnt(8)
	s_waitcnt lgkmcnt(0)
	s_setprio 1
	s_barrier
; #define PG8_STAGE(bufoff, gbase, voff) do { _Pragma("unroll") for (int _i = 0; _i < 2; ++_i) \
;         __builtin_amdgcn_global_load_lds((const unsigned*)((const char*)(gbase) + (voff)[_i]), (PG8_LAS unsigned*)(lds + (bufoff) + ldsw + _i * 8192), 16, 0, 0); } while (0)
; #define PG8_LDA(dst, b, h) do { _Pragma("unroll") for (int m = 0; m < 4; ++m) _Pragma("unroll") for (int k = 0; k < 2; ++k) dst[m][k] = *(const PG8_LAS bf16x8*)(lds + PG8_SA(b, h) + aoff + m * 2048 + k * 1024); } while (0)
; #define PG8_LDB(dst, b, h) do { _Pragma("unroll") for (int n = 0; n < 2; ++n) _Pragma("unroll") for (int k = 0; k < 2; ++k) dst[n][k] = *(const PG8_LAS bf16x8*)(lds + PG8_SB(b, h) + boff + n * 2048 + k * 1024); } while (0)
; #define PG8_MMA(ai, bj, At, Bt) do { __builtin_amdgcn_s_setprio(1); _Pragma("unroll") for (int m = 0; m < 4; ++m) _Pragma("unroll") for (int n = 0; n < 2; ++n) _Pragma("unroll") for (int k = 0; k < 2; ++k) \
;         acc[ai][bj][m][n] = __builtin_amdgcn_mfma_f32_16x16x32_bf16(Bt[n][k], At[m][k], acc[ai][bj][m][n], 0, 0, 0); __builtin_amdgcn_s_setprio(0); } while (0)
; #define PG8_WAIT_V(n) asm volatile("s_waitcnt vmcnt(" #n ")" ::: "memory")
; #define PG8_WAIT_L(n) asm volatile("s_waitcnt lgkmcnt(" #n ")" ::: "memory")
; #define PG8_BAR __builtin_amdgcn_s_barrier()
; #define PG8_SCHED __builtin_amdgcn_sched_barrier(0)
; template <class Epi, class Sched, bool ALIGN_EPI = false, bool SP2 = false>
; __device__ __forceinline__ void gemm_phase(PG8_LAS unsigned char* lds, const Gemm g, const Sched& S, const Epi& E) {
;     ...
;             PG8_WAIT_V(8); PG8_WAIT_L(0); PG8_BAR; PG8_MMA(1, 0, At, B0); PG8_MMA(1, 1, At, B1); PG8_BAR; PG8_SCHED;
;             PG8_LDB(B0, 1, 0); PG8_LDB(B1, 1, 1); PG8_SCHED; PG8_LDA(At, 1, 0); PG8_STAGE(PG8_SA(0, 1), a2 + hstep, voffA);
;             PG8_WAIT_V(8); PG8_WAIT_L(0); PG8_BAR; PG8_MMA(0, 0, At, B0); PG8_MMA(0, 1, At, B1); PG8_BAR; PG8_SCHED;
	v_mfma_f32_16x16x32_bf16 v[60:63], v[128:131], v[190:193], 0
	v_mfma_f32_16x16x32_bf16 v[56:59], v[136:139], v[190:193], 0
	v_mfma_f32_16x16x32_bf16 v[44:47], v[128:131], v[204:207], 0
	v_mfma_f32_16x16x32_bf16 v[40:43], v[136:139], v[204:207], 0
	v_mfma_f32_16x16x32_bf16 v[28:31], v[128:131], v[212:215], 0
	v_mfma_f32_16x16x32_bf16 v[24:27], v[136:139], v[212:215], 0
	v_mfma_f32_16x16x32_bf16 v[12:15], v[128:131], v[220:223], 0
	v_mfma_f32_16x16x32_bf16 v[8:11], v[136:139], v[220:223], 0
	v_mfma_f32_16x16x32_bf16 v[60:63], v[132:135], v[194:197], v[60:63]
	v_mfma_f32_16x16x32_bf16 v[56:59], v[140:143], v[194:197], v[56:59]
	v_mfma_f32_16x16x32_bf16 v[44:47], v[132:135], v[208:211], v[44:47]
	v_mfma_f32_16x16x32_bf16 v[40:43], v[140:143], v[208:211], v[40:43]
	v_mfma_f32_16x16x32_bf16 v[28:31], v[132:135], v[216:219], v[28:31]
	v_mfma_f32_16x16x32_bf16 v[24:27], v[140:143], v[216:219], v[24:27]
	v_mfma_f32_16x16x32_bf16 v[12:15], v[132:135], v[224:227], v[12:15]
	v_mfma_f32_16x16x32_bf16 v[8:11], v[140:143], v[224:227], v[8:11]
	s_setprio 0
	s_setprio 1
	v_mfma_f32_16x16x32_bf16 v[52:55], v[144:147], v[190:193], 0
	v_mfma_f32_16x16x32_bf16 v[48:51], v[182:185], v[190:193], 0
	v_mfma_f32_16x16x32_bf16 v[36:39], v[144:147], v[204:207], 0
	v_mfma_f32_16x16x32_bf16 v[32:35], v[182:185], v[204:207], 0
	v_mfma_f32_16x16x32_bf16 v[20:23], v[144:147], v[212:215], 0
	v_mfma_f32_16x16x32_bf16 v[16:19], v[182:185], v[212:215], 0
	v_mfma_f32_16x16x32_bf16 v[4:7], v[144:147], v[220:223], 0
	v_mfma_f32_16x16x32_bf16 v[0:3], v[182:185], v[220:223], 0
	v_mfma_f32_16x16x32_bf16 v[52:55], v[148:151], v[194:197], v[52:55]
	v_mfma_f32_16x16x32_bf16 v[48:51], v[186:189], v[194:197], v[48:51]
	v_mfma_f32_16x16x32_bf16 v[36:39], v[148:151], v[208:211], v[36:39]
	v_mfma_f32_16x16x32_bf16 v[32:35], v[186:189], v[208:211], v[32:35]
	v_mfma_f32_16x16x32_bf16 v[20:23], v[148:151], v[216:219], v[20:23]
	v_mfma_f32_16x16x32_bf16 v[16:19], v[186:189], v[216:219], v[16:19]
	v_mfma_f32_16x16x32_bf16 v[4:7], v[148:151], v[224:227], v[4:7]
	v_mfma_f32_16x16x32_bf16 v[0:3], v[186:189], v[224:227], v[0:3]
	s_barrier
	s_setprio 0
	s_add_i32 s53, 0, 0x18000
	s_add_i32 s54, 0, 0x1c000
	v_add_u32_e32 v140, s53, v169
	v_add_u32_e32 v186, s54, v169
	ds_read_b128 v[128:131], v140
	ds_read_b128 v[132:135], v140 offset:1024
	ds_read_b128 v[136:139], v140 offset:2048
	ds_read_b128 v[140:143], v140 offset:3072
	ds_read_b128 v[144:147], v186
	ds_read_b128 v[148:151], v186 offset:1024
	ds_read_b128 v[182:185], v186 offset:2048
	ds_read_b128 v[186:189], v186 offset:3072
	s_add_u32 s30, s30, 0x40000
	s_addc_u32 s31, s31, 0
	s_mov_b32 m0, s36
	v_lshl_add_u64 v[248:249], s[30:31], 0, v[156:157]
	ds_read_b128 v[190:193], v202 offset:32768
	ds_read_b128 v[194:197], v202 offset:33792
	ds_read_b128 v[204:207], v202 offset:34816
	ds_read_b128 v[208:211], v202 offset:35840
	ds_read_b128 v[212:215], v202 offset:36864
	ds_read_b128 v[216:219], v202 offset:37888
	ds_read_b128 v[220:223], v202 offset:38912
	ds_read_b128 v[224:227], v202 offset:39936
	global_load_lds_dwordx4 v[248:249], off
	v_lshl_add_u64 v[248:249], s[30:31], 0, v[160:161]
	s_mov_b32 m0, s37
	s_nop 0
	global_load_lds_dwordx4 v[248:249], off
	s_waitcnt vmcnt(8)
	s_waitcnt lgkmcnt(0)
	s_setprio 1
	s_barrier
	v_mfma_f32_16x16x32_bf16 v[124:127], v[128:131], v[190:193], v[124:127]
	v_mfma_f32_16x16x32_bf16 v[120:123], v[136:139], v[190:193], v[120:123]
	v_mfma_f32_16x16x32_bf16 v[108:111], v[128:131], v[204:207], v[108:111]
	v_mfma_f32_16x16x32_bf16 v[104:107], v[136:139], v[204:207], v[104:107]
	v_mfma_f32_16x16x32_bf16 v[92:95], v[128:131], v[212:215], v[92:95]
	v_mfma_f32_16x16x32_bf16 v[88:91], v[136:139], v[212:215], v[88:91]
	v_mfma_f32_16x16x32_bf16 v[76:79], v[128:131], v[220:223], v[76:79]
	v_mfma_f32_16x16x32_bf16 v[72:75], v[136:139], v[220:223], v[72:75]
	v_mfma_f32_16x16x32_bf16 v[124:127], v[132:135], v[194:197], v[124:127]
	v_mfma_f32_16x16x32_bf16 v[120:123], v[140:143], v[194:197], v[120:123]
	v_mfma_f32_16x16x32_bf16 v[108:111], v[132:135], v[208:211], v[108:111]
	v_mfma_f32_16x16x32_bf16 v[104:107], v[140:143], v[208:211], v[104:107]
	v_mfma_f32_16x16x32_bf16 v[92:95], v[132:135], v[216:219], v[92:95]
	v_mfma_f32_16x16x32_bf16 v[88:91], v[140:143], v[216:219], v[88:91]
	v_mfma_f32_16x16x32_bf16 v[76:79], v[132:135], v[224:227], v[76:79]
	v_mfma_f32_16x16x32_bf16 v[72:75], v[140:143], v[224:227], v[72:75]
	s_setprio 0
	s_setprio 1
	v_mfma_f32_16x16x32_bf16 v[116:119], v[144:147], v[190:193], v[116:119]
	v_mfma_f32_16x16x32_bf16 v[112:115], v[182:185], v[190:193], v[112:115]
	v_mfma_f32_16x16x32_bf16 v[100:103], v[144:147], v[204:207], v[100:103]
	v_mfma_f32_16x16x32_bf16 v[96:99], v[182:185], v[204:207], v[96:99]
	v_mfma_f32_16x16x32_bf16 v[84:87], v[144:147], v[212:215], v[84:87]
	v_mfma_f32_16x16x32_bf16 v[80:83], v[182:185], v[212:215], v[80:83]
	v_mfma_f32_16x16x32_bf16 v[68:71], v[144:147], v[220:223], v[68:71]
	v_mfma_f32_16x16x32_bf16 v[64:67], v[182:185], v[220:223], v[64:67]
	v_mfma_f32_16x16x32_bf16 v[116:119], v[148:151], v[194:197], v[116:119]
	v_mfma_f32_16x16x32_bf16 v[112:115], v[186:189], v[194:197], v[112:115]
	v_mfma_f32_16x16x32_bf16 v[100:103], v[148:151], v[208:211], v[100:103]
	v_mfma_f32_16x16x32_bf16 v[96:99], v[186:189], v[208:211], v[96:99]
	v_mfma_f32_16x16x32_bf16 v[84:87], v[148:151], v[216:219], v[84:87]
	v_mfma_f32_16x16x32_bf16 v[80:83], v[186:189], v[216:219], v[80:83]
	v_mfma_f32_16x16x32_bf16 v[68:71], v[148:151], v[224:227], v[68:71]
	v_mfma_f32_16x16x32_bf16 v[64:67], v[186:189], v[224:227], v[64:67]
	s_barrier
; #define PG8_STAGE(bufoff, gbase, voff) do { _Pragma("unroll") for (int _i = 0; _i < 2; ++_i) \
;         __builtin_amdgcn_global_load_lds((const unsigned*)((const char*)(gbase) + (voff)[_i]), (PG8_LAS unsigned*)(lds + (bufoff) + ldsw + _i * 8192), 16, 0, 0); } while (0)
; #define PG8_LDA(dst, b, h) do { _Pragma("unroll") for (int m = 0; m < 4; ++m) _Pragma("unroll") for (int k = 0; k < 2; ++k) dst[m][k] = *(const PG8_LAS bf16x8*)(lds + PG8_SA(b, h) + aoff + m * 2048 + k * 1024); } while (0)
; #define PG8_MMA(ai, bj, At, Bt) do { __builtin_amdgcn_s_setprio(1); _Pragma("unroll") for (int m = 0; m < 4; ++m) _Pragma("unroll") for (int n = 0; n < 2; ++n) _Pragma("unroll") for (int k = 0; k < 2; ++k) \
;         acc[ai][bj][m][n] = __builtin_amdgcn_mfma_f32_16x16x32_bf16(Bt[n][k], At[m][k], acc[ai][bj][m][n], 0, 0, 0); __builtin_amdgcn_s_setprio(0); } while (0)
; #define PG8_WAIT_V(n) asm volatile("s_waitcnt vmcnt(" #n ")" ::: "memory")
; #define PG8_WAIT_L(n) asm volatile("s_waitcnt lgkmcnt(" #n ")" ::: "memory")
; #define PG8_BAR __builtin_amdgcn_s_barrier()
; #define PG8_SCHED __builtin_amdgcn_sched_barrier(0)
; template <class Epi, class Sched, bool ALIGN_EPI = false, bool SP2 = false>
; __device__ __forceinline__ void gemm_phase(PG8_LAS unsigned char* lds, const Gemm g, const Sched& S, const Epi& E) {
;     ...
;         for (int t = 0; t < nt; t += 2) {
;             const bool last = (t == nt - 2);
;     ...
;             PG8_LDA(At, 1, 1); PG8_STAGE(PG8_SB(1, 0), b3, voffB); PG8_STAGE(PG8_SB(1, 1), b3 + hstep, voffB); PG8_STAGE(PG8_SA(1, 0), a3, voffA);
;             PG8_WAIT_V(8); PG8_WAIT_L(0); PG8_BAR; PG8_MMA(1, 0, At, B0); PG8_MMA(1, 1, At, B1); PG8_BAR; PG8_SCHED;
	s_setprio 0
	s_add_i32 s30, s53, s33
	v_lshl_add_u64 v[198:199], v[198:199], 0, s[6:7]
	s_mov_b32 m0, s30
	ds_read_b128 v[190:193], v202 offset:49152
	ds_read_b128 v[194:197], v202 offset:50176
	ds_read_b128 v[204:207], v202 offset:51200
	ds_read_b128 v[208:211], v202 offset:52224
	ds_read_b128 v[212:215], v202 offset:53248
	ds_read_b128 v[216:219], v202 offset:54272
	ds_read_b128 v[220:223], v202 offset:55296
	ds_read_b128 v[224:227], v202 offset:56320
	global_load_lds_dwordx4 v[198:199], off
	s_add_i32 m0, s30, 0x2000
	s_add_u32 s28, s28, 0x40080
	v_lshl_add_u64 v[198:199], v[228:229], 0, s[6:7]
	s_addc_u32 s29, s29, 0
	s_add_i32 s30, s54, s33
	global_load_lds_dwordx4 v[198:199], off
	v_lshl_add_u64 v[198:199], s[28:29], 0, v[158:159]
	s_mov_b32 m0, s30
	s_nop 0
	global_load_lds_dwordx4 v[198:199], off
	v_lshl_add_u64 v[198:199], s[28:29], 0, v[162:163]
	s_add_i32 m0, s30, 0x2000
	s_nop 0
	global_load_lds_dwordx4 v[198:199], off
	v_lshl_add_u64 v[198:199], v[238:239], 0, s[6:7]
	s_mov_b32 m0, s39
	s_nop 0
	global_load_lds_dwordx4 v[198:199], off
	v_lshl_add_u64 v[198:199], v[246:247], 0, s[6:7]
	s_mov_b32 m0, s40
	s_nop 0
	global_load_lds_dwordx4 v[198:199], off
	s_waitcnt vmcnt(8)
	s_waitcnt lgkmcnt(0)
	s_setprio 1
	s_barrier
	v_mfma_f32_16x16x32_bf16 v[60:63], v[128:131], v[190:193], v[60:63]
	v_mfma_f32_16x16x32_bf16 v[56:59], v[136:139], v[190:193], v[56:59]
	v_mfma_f32_16x16x32_bf16 v[44:47], v[128:131], v[204:207], v[44:47]
	v_mfma_f32_16x16x32_bf16 v[40:43], v[136:139], v[204:207], v[40:43]
	v_mfma_f32_16x16x32_bf16 v[28:31], v[128:131], v[212:215], v[28:31]
	v_mfma_f32_16x16x32_bf16 v[24:27], v[136:139], v[212:215], v[24:27]
	v_mfma_f32_16x16x32_bf16 v[12:15], v[128:131], v[220:223], v[12:15]
	v_mfma_f32_16x16x32_bf16 v[8:11], v[136:139], v[220:223], v[8:11]
	v_mfma_f32_16x16x32_bf16 v[60:63], v[132:135], v[194:197], v[60:63]
	v_mfma_f32_16x16x32_bf16 v[56:59], v[140:143], v[194:197], v[56:59]
	v_mfma_f32_16x16x32_bf16 v[44:47], v[132:135], v[208:211], v[44:47]
	v_mfma_f32_16x16x32_bf16 v[40:43], v[140:143], v[208:211], v[40:43]
	v_mfma_f32_16x16x32_bf16 v[28:31], v[132:135], v[216:219], v[28:31]
	v_mfma_f32_16x16x32_bf16 v[24:27], v[140:143], v[216:219], v[24:27]
	v_mfma_f32_16x16x32_bf16 v[12:15], v[132:135], v[224:227], v[12:15]
	v_mfma_f32_16x16x32_bf16 v[8:11], v[140:143], v[224:227], v[8:11]
	s_setprio 0
	s_setprio 1
	v_mfma_f32_16x16x32_bf16 v[52:55], v[144:147], v[190:193], v[52:55]
	v_mfma_f32_16x16x32_bf16 v[48:51], v[182:185], v[190:193], v[48:51]
	v_mfma_f32_16x16x32_bf16 v[36:39], v[144:147], v[204:207], v[36:39]
	v_mfma_f32_16x16x32_bf16 v[32:35], v[182:185], v[204:207], v[32:35]
	v_mfma_f32_16x16x32_bf16 v[20:23], v[144:147], v[212:215], v[20:23]
	v_mfma_f32_16x16x32_bf16 v[16:19], v[182:185], v[212:215], v[16:19]
	v_mfma_f32_16x16x32_bf16 v[4:7], v[144:147], v[220:223], v[4:7]
	v_mfma_f32_16x16x32_bf16 v[0:3], v[182:185], v[220:223], v[0:3]
	v_mfma_f32_16x16x32_bf16 v[52:55], v[148:151], v[194:197], v[52:55]
	v_mfma_f32_16x16x32_bf16 v[48:51], v[186:189], v[194:197], v[48:51]
	v_mfma_f32_16x16x32_bf16 v[36:39], v[148:151], v[208:211], v[36:39]
	v_mfma_f32_16x16x32_bf16 v[32:35], v[186:189], v[208:211], v[32:35]
	v_mfma_f32_16x16x32_bf16 v[20:23], v[148:151], v[216:219], v[20:23]
	v_mfma_f32_16x16x32_bf16 v[16:19], v[186:189], v[216:219], v[16:19]
	v_mfma_f32_16x16x32_bf16 v[4:7], v[148:151], v[224:227], v[4:7]
	v_mfma_f32_16x16x32_bf16 v[0:3], v[186:189], v[224:227], v[0:3]
	s_barrier
	s_setprio 0
	s_add_i32 s52, s52, 2
	s_add_u32 s26, s26, 0x100
	s_addc_u32 s27, s27, 0
	s_add_u32 s50, s50, 0x100
	s_addc_u32 s51, s51, 0
	s_cmp_gt_u32 s52, 13
	s_cbranch_scc1 .Lpeel_done_g3
	.p2align	6

; #define PG8_STAGE(bufoff, gbase, voff) do { _Pragma("unroll") for (int _i = 0; _i < 2; ++_i) \
;         __builtin_amdgcn_global_load_lds((const unsigned*)((const char*)(gbase) + (voff)[_i]), (PG8_LAS unsigned*)(lds + (bufoff) + ldsw + _i * 8192), 16, 0, 0); } while (0)
; #define PG8_LDA(dst, b, h) do { _Pragma("unroll") for (int m = 0; m < 4; ++m) _Pragma("unroll") for (int k = 0; k < 2; ++k) dst[m][k] = *(const PG8_LAS bf16x8*)(lds + PG8_SA(b, h) + aoff + m * 2048 + k * 1024); } while (0)
; #define PG8_LDB(dst, b, h) do { _Pragma("unroll") for (int n = 0; n < 2; ++n) _Pragma("unroll") for (int k = 0; k < 2; ++k) dst[n][k] = *(const PG8_LAS bf16x8*)(lds + PG8_SB(b, h) + boff + n * 2048 + k * 1024); } while (0)
; #define PG8_MMA(ai, bj, At, Bt) do { __builtin_amdgcn_s_setprio(1); _Pragma("unroll") for (int m = 0; m < 4; ++m) _Pragma("unroll") for (int n = 0; n < 2; ++n) _Pragma("unroll") for (int k = 0; k < 2; ++k) \
;         acc[ai][bj][m][n] = __builtin_amdgcn_mfma_f32_16x16x32_bf16(Bt[n][k], At[m][k], acc[ai][bj][m][n], 0, 0, 0); __builtin_amdgcn_s_setprio(0); } while (0)
; #define PG8_BAR __builtin_amdgcn_s_barrier()
; template <class Epi, class Sched, bool ALIGN_EPI = false, bool SP2 = false>
; __device__ __forceinline__ void gemm_phase(PG8_LAS unsigned char* lds, const Gemm g, const Sched& S, const Epi& E) {
;     ...
;         const bool has_next = S.next(ui + 1, nxt);
;         const char* nA = has_next ? (const char*)g.A + (size_t)nxt.pm * tstep : cA; const char* nB = has_next ? (const char*)g.Bt + (size_t)nxt.pn * tstep : cB;
;         for (int t = 0; t < nt; t += 2) {
;             const bool last = (t == nt - 2);
;             const char* a1 = cA + (size_t)(t + 1) * kstep;
;             const char* a2 = last ? nA : cA + (size_t)(t + 2) * kstep; const char* b2 = last ? nB : cB + (size_t)(t + 2) * kstep;
;             const char* a3 = a2 + kstep; const char* b3 = b2 + kstep;
;             if (last && has_next) S.a_ready(nxt);
;             if constexpr (SP2) {
;             PG8_LDB(B0, 0, 0); PG8_LDB(B1, 0, 1); PG8_SCHED; PG8_LDA(At, 0, 0); PG8_STAGE(PG8_SA(1, 1), a1 + hstep, voffA);
;             PG8_WAIT_V(8); PG8_WAIT_L(0); PG8_BAR; PG8_MMA(0, 0, At, B0); PG8_MMA(0, 1, At, B1); PG8_BAR; PG8_SCHED;
;             PG8_LDA(At, 0, 1); PG8_STAGE(PG8_SB(0, 0), b2, voffB); PG8_STAGE(PG8_SB(0, 1), b2 + hstep, voffB); PG8_STAGE(PG8_SA(0, 0), a2, voffA);
.LBB0_1321:
	s_ashr_i32 s19, s18, 31
	s_lshl_b64 s[20:21], s[18:19], 19
	s_add_u32 s20, s76, s20
	s_addc_u32 s21, s77, s21
	s_and_b64 s[22:23], s[8:9], exec
	s_cselect_b32 s1, s21, s25
	s_cselect_b32 s11, s20, s24
	s_ashr_i32 s17, s16, 31
	s_lshl_b64 s[22:23], s[16:17], 19
	s_add_u32 s22, s30, s22
	s_addc_u32 s23, s31, s23
	s_and_b64 s[28:29], s[8:9], exec
	s_cselect_b32 s17, s23, s27
	s_cselect_b32 s19, s22, s26
	s_add_u32 s24, s24, 0x40080
	s_addc_u32 s25, s25, 0
	s_add_u32 s48, s26, 0x100
	s_addc_u32 s49, s27, 0
	s_mov_b32 s50, -2
	ds_read_b128 v[136:139], v144
	ds_read_b128 v[174:177], v144 offset:1024
	ds_read_b128 v[178:181], v144 offset:2048
	ds_read_b128 v[182:185], v144 offset:3072
	ds_read_b128 v[186:189], v145
	ds_read_b128 v[190:193], v145 offset:1024
	ds_read_b128 v[194:197], v145 offset:2048
	ds_read_b128 v[198:201], v145 offset:3072
	s_add_u32 s26, s24, 0xfffc0080
	s_addc_u32 s27, s25, -1
	s_cmp_eq_u32 s50, 12
	s_cselect_b32 s29, s1, s27
	s_cselect_b32 s28, s11, s26
	s_cselect_b32 s27, s17, s49
	s_cselect_b32 s26, s19, s48
	v_lshl_add_u64 v[150:151], s[24:25], 0, v[128:129]
	s_add_i32 m0, s33, 0xc000
	ds_read_b128 v[202:205], v146
	ds_read_b128 v[206:209], v146 offset:1024
	ds_read_b128 v[210:213], v146 offset:2048
	ds_read_b128 v[214:217], v146 offset:3072
	ds_read_b128 v[218:221], v146 offset:4096
	ds_read_b128 v[222:225], v146 offset:5120
	ds_read_b128 v[226:229], v146 offset:6144
	ds_read_b128 v[236:239], v146 offset:7168
	global_load_lds_dwordx4 v[150:151], off
	v_lshl_add_u64 v[150:151], s[24:25], 0, v[130:131]
	s_add_i32 m0, s33, 0xe000
	s_nop 0
	global_load_lds_dwordx4 v[150:151], off
	s_waitcnt vmcnt(8)
	s_waitcnt lgkmcnt(0)
	s_setprio 1
	s_barrier
	v_mfma_f32_16x16x32_bf16 v[124:127], v[136:139], v[202:205], 0
	v_mfma_f32_16x16x32_bf16 v[116:119], v[178:181], v[202:205], 0
	v_mfma_f32_16x16x32_bf16 v[108:111], v[136:139], v[210:213], 0
	v_mfma_f32_16x16x32_bf16 v[100:103], v[178:181], v[210:213], 0
	v_mfma_f32_16x16x32_bf16 v[92:95], v[136:139], v[218:221], 0
	v_mfma_f32_16x16x32_bf16 v[84:87], v[178:181], v[218:221], 0
	v_mfma_f32_16x16x32_bf16 v[76:79], v[136:139], v[226:229], 0
	v_mfma_f32_16x16x32_bf16 v[68:71], v[178:181], v[226:229], 0
	v_mfma_f32_16x16x32_bf16 v[124:127], v[174:177], v[206:209], v[124:127]
	v_mfma_f32_16x16x32_bf16 v[116:119], v[182:185], v[206:209], v[116:119]
	v_mfma_f32_16x16x32_bf16 v[108:111], v[174:177], v[214:217], v[108:111]
	v_mfma_f32_16x16x32_bf16 v[100:103], v[182:185], v[214:217], v[100:103]
	v_mfma_f32_16x16x32_bf16 v[92:95], v[174:177], v[222:225], v[92:95]
	v_mfma_f32_16x16x32_bf16 v[84:87], v[182:185], v[222:225], v[84:87]
	v_mfma_f32_16x16x32_bf16 v[76:79], v[174:177], v[236:239], v[76:79]
	v_mfma_f32_16x16x32_bf16 v[68:71], v[182:185], v[236:239], v[68:71]
	s_setprio 0
	s_setprio 1
	v_mfma_f32_16x16x32_bf16 v[120:123], v[186:189], v[202:205], 0
	v_mfma_f32_16x16x32_bf16 v[112:115], v[194:197], v[202:205], 0
	v_mfma_f32_16x16x32_bf16 v[104:107], v[186:189], v[210:213], 0
	v_mfma_f32_16x16x32_bf16 v[96:99], v[194:197], v[210:213], 0
	v_mfma_f32_16x16x32_bf16 v[88:91], v[186:189], v[218:221], 0
	v_mfma_f32_16x16x32_bf16 v[80:83], v[194:197], v[218:221], 0
	v_mfma_f32_16x16x32_bf16 v[72:75], v[186:189], v[226:229], 0
	v_mfma_f32_16x16x32_bf16 v[64:67], v[194:197], v[226:229], 0
	v_mfma_f32_16x16x32_bf16 v[120:123], v[190:193], v[206:209], v[120:123]
	v_mfma_f32_16x16x32_bf16 v[112:115], v[198:201], v[206:209], v[112:115]
	v_mfma_f32_16x16x32_bf16 v[104:107], v[190:193], v[214:217], v[104:107]
	v_mfma_f32_16x16x32_bf16 v[96:99], v[198:201], v[214:217], v[96:99]
	v_mfma_f32_16x16x32_bf16 v[88:91], v[190:193], v[222:225], v[88:91]
	v_mfma_f32_16x16x32_bf16 v[80:83], v[198:201], v[222:225], v[80:83]
	v_mfma_f32_16x16x32_bf16 v[72:75], v[190:193], v[236:239], v[72:75]
	v_mfma_f32_16x16x32_bf16 v[64:67], v[198:201], v[236:239], v[64:67]
	s_barrier
	s_setprio 0
	s_add_i32 s51, s44, s3
	v_lshl_add_u64 v[150:151], s[26:27], 0, v[158:159]
	s_mov_b32 m0, s51
	ds_read_b128 v[202:205], v146 offset:16384
	ds_read_b128 v[206:209], v146 offset:17408
	ds_read_b128 v[210:213], v146 offset:18432
	ds_read_b128 v[214:217], v146 offset:19456
	ds_read_b128 v[218:221], v146 offset:20480
	ds_read_b128 v[222:225], v146 offset:21504
	ds_read_b128 v[226:229], v146 offset:22528
	ds_read_b128 v[236:239], v146 offset:23552
	global_load_lds_dwordx4 v[150:151], off
	s_add_i32 m0, s51, 0x2000
	s_add_u32 s52, s26, 0x40000
	v_lshl_add_u64 v[246:247], s[26:27], 0, v[162:163]
	s_addc_u32 s53, s27, 0
	s_add_i32 s51, s45, s3
	global_load_lds_dwordx4 v[246:247], off
	v_lshl_add_u64 v[248:249], s[52:53], 0, v[158:159]
	s_mov_b32 m0, s51
	v_lshl_add_u64 v[250:251], s[28:29], 0, v[160:161]
	global_load_lds_dwordx4 v[248:249], off
	v_lshl_add_u64 v[248:249], s[52:53], 0, v[162:163]
	s_add_i32 m0, s51, 0x2000
	s_nop 0
	global_load_lds_dwordx4 v[248:249], off
	v_lshl_add_u64 v[248:249], s[28:29], 0, v[156:157]
	s_mov_b32 m0, s33
	s_nop 0
	global_load_lds_dwordx4 v[248:249], off
	s_mov_b32 m0, s34
	s_nop 0
	global_load_lds_dwordx4 v[250:251], off
	s_waitcnt vmcnt(8)
	s_waitcnt lgkmcnt(0)
	s_setprio 1
	s_barrier
; #define PG8_STAGE(bufoff, gbase, voff) do { _Pragma("unroll") for (int _i = 0; _i < 2; ++_i) \
;         __builtin_amdgcn_global_load_lds((const unsigned*)((const char*)(gbase) + (voff)[_i]), (PG8_LAS unsigned*)(lds + (bufoff) + ldsw + _i * 8192), 16, 0, 0); } while (0)
; #define PG8_LDA(dst, b, h) do { _Pragma("unroll") for (int m = 0; m < 4; ++m) _Pragma("unroll") for (int k = 0; k < 2; ++k) dst[m][k] = *(const PG8_LAS bf16x8*)(lds + PG8_SA(b, h) + aoff + m * 2048 + k * 1024); } while (0)
; #define PG8_LDB(dst, b, h) do { _Pragma("unroll") for (int n = 0; n < 2; ++n) _Pragma("unroll") for (int k = 0; k < 2; ++k) dst[n][k] = *(const PG8_LAS bf16x8*)(lds + PG8_SB(b, h) + boff + n * 2048 + k * 1024); } while (0)
; #define PG8_MMA(ai, bj, At, Bt) do { __builtin_amdgcn_s_setprio(1); _Pragma("unroll") for (int m = 0; m < 4; ++m) _Pragma("unroll") for (int n = 0; n < 2; ++n) _Pragma("unroll") for (int k = 0; k < 2; ++k) \
;         acc[ai][bj][m][n] = __builtin_amdgcn_mfma_f32_16x16x32_bf16(Bt[n][k], At[m][k], acc[ai][bj][m][n], 0, 0, 0); __builtin_amdgcn_s_setprio(0); } while (0)
; #define PG8_WAIT_V(n) asm volatile("s_waitcnt vmcnt(" #n ")" ::: "memory")
; #define PG8_WAIT_L(n) asm volatile("s_waitcnt lgkmcnt(" #n ")" ::: "memory")
; #define PG8_BAR __builtin_amdgcn_s_barrier()
; #define PG8_SCHED __builtin_amdgcn_sched_barrier(0)
; template <class Epi, class Sched, bool ALIGN_EPI = false, bool SP2 = false>
; __device__ __forceinline__ void gemm_phase(PG8_LAS unsigned char* lds, const Gemm g, const Sched& S, const Epi& E) {
;     ...
;             PG8_WAIT_V(8); PG8_WAIT_L(0); PG8_BAR; PG8_MMA(1, 0, At, B0); PG8_MMA(1, 1, At, B1); PG8_BAR; PG8_SCHED;
;             PG8_LDB(B0, 1, 0); PG8_LDB(B1, 1, 1); PG8_SCHED; PG8_LDA(At, 1, 0); PG8_STAGE(PG8_SA(0, 1), a2 + hstep, voffA);
;             PG8_WAIT_V(8); PG8_WAIT_L(0); PG8_BAR; PG8_MMA(0, 0, At, B0); PG8_MMA(0, 1, At, B1); PG8_BAR; PG8_SCHED;
	v_mfma_f32_16x16x32_bf16 v[60:63], v[136:139], v[202:205], 0
	v_mfma_f32_16x16x32_bf16 v[52:55], v[178:181], v[202:205], 0
	v_mfma_f32_16x16x32_bf16 v[44:47], v[136:139], v[210:213], 0
	v_mfma_f32_16x16x32_bf16 v[36:39], v[178:181], v[210:213], 0
	v_mfma_f32_16x16x32_bf16 v[28:31], v[136:139], v[218:221], 0
	v_mfma_f32_16x16x32_bf16 v[20:23], v[178:181], v[218:221], 0
	v_mfma_f32_16x16x32_bf16 v[12:15], v[136:139], v[226:229], 0
	v_mfma_f32_16x16x32_bf16 v[4:7], v[178:181], v[226:229], 0
	v_mfma_f32_16x16x32_bf16 v[60:63], v[174:177], v[206:209], v[60:63]
	v_mfma_f32_16x16x32_bf16 v[52:55], v[182:185], v[206:209], v[52:55]
	v_mfma_f32_16x16x32_bf16 v[44:47], v[174:177], v[214:217], v[44:47]
	v_mfma_f32_16x16x32_bf16 v[36:39], v[182:185], v[214:217], v[36:39]
	v_mfma_f32_16x16x32_bf16 v[28:31], v[174:177], v[222:225], v[28:31]
	v_mfma_f32_16x16x32_bf16 v[20:23], v[182:185], v[222:225], v[20:23]
	v_mfma_f32_16x16x32_bf16 v[12:15], v[174:177], v[236:239], v[12:15]
	v_mfma_f32_16x16x32_bf16 v[4:7], v[182:185], v[236:239], v[4:7]
	s_setprio 0
	s_setprio 1
	v_mfma_f32_16x16x32_bf16 v[56:59], v[186:189], v[202:205], 0
	v_mfma_f32_16x16x32_bf16 v[48:51], v[194:197], v[202:205], 0
	v_mfma_f32_16x16x32_bf16 v[40:43], v[186:189], v[210:213], 0
	v_mfma_f32_16x16x32_bf16 v[32:35], v[194:197], v[210:213], 0
	v_mfma_f32_16x16x32_bf16 v[24:27], v[186:189], v[218:221], 0
	v_mfma_f32_16x16x32_bf16 v[16:19], v[194:197], v[218:221], 0
	v_mfma_f32_16x16x32_bf16 v[8:11], v[186:189], v[226:229], 0
	v_mfma_f32_16x16x32_bf16 v[0:3], v[194:197], v[226:229], 0
	v_mfma_f32_16x16x32_bf16 v[56:59], v[190:193], v[206:209], v[56:59]
	v_mfma_f32_16x16x32_bf16 v[48:51], v[198:201], v[206:209], v[48:51]
	v_mfma_f32_16x16x32_bf16 v[40:43], v[190:193], v[214:217], v[40:43]
	v_mfma_f32_16x16x32_bf16 v[32:35], v[198:201], v[214:217], v[32:35]
	v_mfma_f32_16x16x32_bf16 v[24:27], v[190:193], v[222:225], v[24:27]
	v_mfma_f32_16x16x32_bf16 v[16:19], v[198:201], v[222:225], v[16:19]
	v_mfma_f32_16x16x32_bf16 v[8:11], v[190:193], v[236:239], v[8:11]
	v_mfma_f32_16x16x32_bf16 v[0:3], v[198:201], v[236:239], v[0:3]
	s_barrier
	s_setprio 0
	s_add_i32 s51, 0, 0x18000
	v_add_u32_e32 v149, s51, v141
	s_add_i32 s52, 0, 0x1c000
	ds_read_b128 v[136:139], v149
	ds_read_b128 v[174:177], v149 offset:1024
	ds_read_b128 v[178:181], v149 offset:2048
	ds_read_b128 v[182:185], v149 offset:3072
	v_add_u32_e32 v149, s52, v141
	ds_read_b128 v[186:189], v149
	ds_read_b128 v[190:193], v149 offset:1024
	ds_read_b128 v[194:197], v149 offset:2048
	ds_read_b128 v[198:201], v149 offset:3072
	s_add_u32 s28, s28, 0x40000
	s_addc_u32 s29, s29, 0
	s_mov_b32 m0, s35
	v_lshl_add_u64 v[252:253], s[28:29], 0, v[156:157]
	ds_read_b128 v[202:205], v146 offset:32768
	ds_read_b128 v[206:209], v146 offset:33792
	ds_read_b128 v[210:213], v146 offset:34816
	ds_read_b128 v[214:217], v146 offset:35840
	ds_read_b128 v[218:221], v146 offset:36864
	ds_read_b128 v[222:225], v146 offset:37888
	ds_read_b128 v[226:229], v146 offset:38912
	ds_read_b128 v[236:239], v146 offset:39936
	global_load_lds_dwordx4 v[252:253], off
	v_lshl_add_u64 v[252:253], s[28:29], 0, v[160:161]
	s_mov_b32 m0, s36
	s_nop 0
	global_load_lds_dwordx4 v[252:253], off
	s_waitcnt vmcnt(8)
	s_waitcnt lgkmcnt(0)
	s_setprio 1
	s_barrier
	v_mfma_f32_16x16x32_bf16 v[124:127], v[136:139], v[202:205], v[124:127]
	v_mfma_f32_16x16x32_bf16 v[116:119], v[178:181], v[202:205], v[116:119]
	v_mfma_f32_16x16x32_bf16 v[108:111], v[136:139], v[210:213], v[108:111]
	v_mfma_f32_16x16x32_bf16 v[100:103], v[178:181], v[210:213], v[100:103]
	v_mfma_f32_16x16x32_bf16 v[92:95], v[136:139], v[218:221], v[92:95]
	v_mfma_f32_16x16x32_bf16 v[84:87], v[178:181], v[218:221], v[84:87]
	v_mfma_f32_16x16x32_bf16 v[76:79], v[136:139], v[226:229], v[76:79]
	v_mfma_f32_16x16x32_bf16 v[68:71], v[178:181], v[226:229], v[68:71]
	v_mfma_f32_16x16x32_bf16 v[124:127], v[174:177], v[206:209], v[124:127]
	v_mfma_f32_16x16x32_bf16 v[116:119], v[182:185], v[206:209], v[116:119]
	v_mfma_f32_16x16x32_bf16 v[108:111], v[174:177], v[214:217], v[108:111]
	v_mfma_f32_16x16x32_bf16 v[100:103], v[182:185], v[214:217], v[100:103]
	v_mfma_f32_16x16x32_bf16 v[92:95], v[174:177], v[222:225], v[92:95]
	v_mfma_f32_16x16x32_bf16 v[84:87], v[182:185], v[222:225], v[84:87]
	v_mfma_f32_16x16x32_bf16 v[76:79], v[174:177], v[236:239], v[76:79]
	v_mfma_f32_16x16x32_bf16 v[68:71], v[182:185], v[236:239], v[68:71]
	s_setprio 0
	s_setprio 1
	v_mfma_f32_16x16x32_bf16 v[120:123], v[186:189], v[202:205], v[120:123]
	v_mfma_f32_16x16x32_bf16 v[112:115], v[194:197], v[202:205], v[112:115]
	v_mfma_f32_16x16x32_bf16 v[104:107], v[186:189], v[210:213], v[104:107]
	v_mfma_f32_16x16x32_bf16 v[96:99], v[194:197], v[210:213], v[96:99]
	v_mfma_f32_16x16x32_bf16 v[88:91], v[186:189], v[218:221], v[88:91]
	v_mfma_f32_16x16x32_bf16 v[80:83], v[194:197], v[218:221], v[80:83]
	v_mfma_f32_16x16x32_bf16 v[72:75], v[186:189], v[226:229], v[72:75]
	v_mfma_f32_16x16x32_bf16 v[64:67], v[194:197], v[226:229], v[64:67]
	v_mfma_f32_16x16x32_bf16 v[120:123], v[190:193], v[206:209], v[120:123]
	v_mfma_f32_16x16x32_bf16 v[112:115], v[198:201], v[206:209], v[112:115]
	v_mfma_f32_16x16x32_bf16 v[104:107], v[190:193], v[214:217], v[104:107]
	v_mfma_f32_16x16x32_bf16 v[96:99], v[198:201], v[214:217], v[96:99]
	v_mfma_f32_16x16x32_bf16 v[88:91], v[190:193], v[222:225], v[88:91]
	v_mfma_f32_16x16x32_bf16 v[80:83], v[198:201], v[222:225], v[80:83]
	v_mfma_f32_16x16x32_bf16 v[72:75], v[190:193], v[236:239], v[72:75]
	v_mfma_f32_16x16x32_bf16 v[64:67], v[198:201], v[236:239], v[64:67]
	s_barrier
; #define PG8_STAGE(bufoff, gbase, voff) do { _Pragma("unroll") for (int _i = 0; _i < 2; ++_i) \
;         __builtin_amdgcn_global_load_lds((const unsigned*)((const char*)(gbase) + (voff)[_i]), (PG8_LAS unsigned*)(lds + (bufoff) + ldsw + _i * 8192), 16, 0, 0); } while (0)
; #define PG8_LDA(dst, b, h) do { _Pragma("unroll") for (int m = 0; m < 4; ++m) _Pragma("unroll") for (int k = 0; k < 2; ++k) dst[m][k] = *(const PG8_LAS bf16x8*)(lds + PG8_SA(b, h) + aoff + m * 2048 + k * 1024); } while (0)
; #define PG8_MMA(ai, bj, At, Bt) do { __builtin_amdgcn_s_setprio(1); _Pragma("unroll") for (int m = 0; m < 4; ++m) _Pragma("unroll") for (int n = 0; n < 2; ++n) _Pragma("unroll") for (int k = 0; k < 2; ++k) \
;         acc[ai][bj][m][n] = __builtin_amdgcn_mfma_f32_16x16x32_bf16(Bt[n][k], At[m][k], acc[ai][bj][m][n], 0, 0, 0); __builtin_amdgcn_s_setprio(0); } while (0)
; #define PG8_WAIT_V(n) asm volatile("s_waitcnt vmcnt(" #n ")" ::: "memory")
; #define PG8_WAIT_L(n) asm volatile("s_waitcnt lgkmcnt(" #n ")" ::: "memory")
; #define PG8_BAR __builtin_amdgcn_s_barrier()
; #define PG8_SCHED __builtin_amdgcn_sched_barrier(0)
; template <class Epi, class Sched, bool ALIGN_EPI = false, bool SP2 = false>
; __device__ __forceinline__ void gemm_phase(PG8_LAS unsigned char* lds, const Gemm g, const Sched& S, const Epi& E) {
;     ...
;         for (int t = 0; t < nt; t += 2) {
;             const bool last = (t == nt - 2);
;     ...
;             PG8_LDA(At, 1, 1); PG8_STAGE(PG8_SB(1, 0), b3, voffB); PG8_STAGE(PG8_SB(1, 1), b3 + hstep, voffB); PG8_STAGE(PG8_SA(1, 0), a3, voffA);
;             PG8_WAIT_V(8); PG8_WAIT_L(0); PG8_BAR; PG8_MMA(1, 0, At, B0); PG8_MMA(1, 1, At, B1); PG8_BAR; PG8_SCHED;
	s_setprio 0
	s_add_i32 s28, s51, s3
	v_lshl_add_u64 v[150:151], v[150:151], 0, s[6:7]
	s_mov_b32 m0, s28
	ds_read_b128 v[202:205], v146 offset:49152
	ds_read_b128 v[206:209], v146 offset:50176
	ds_read_b128 v[210:213], v146 offset:51200
	ds_read_b128 v[214:217], v146 offset:52224
	ds_read_b128 v[218:221], v146 offset:53248
	ds_read_b128 v[222:225], v146 offset:54272
	ds_read_b128 v[226:229], v146 offset:55296
	ds_read_b128 v[236:239], v146 offset:56320
	global_load_lds_dwordx4 v[150:151], off
	s_add_i32 m0, s28, 0x2000
	s_add_u32 s26, s26, 0x40080
	v_lshl_add_u64 v[150:151], v[246:247], 0, s[6:7]
	s_addc_u32 s27, s27, 0
	s_add_i32 s28, s52, s3
	global_load_lds_dwordx4 v[150:151], off
	v_lshl_add_u64 v[150:151], s[26:27], 0, v[158:159]
	s_mov_b32 m0, s28
	s_nop 0
	global_load_lds_dwordx4 v[150:151], off
	v_lshl_add_u64 v[150:151], s[26:27], 0, v[162:163]
	s_add_i32 m0, s28, 0x2000
	s_nop 0
	global_load_lds_dwordx4 v[150:151], off
	v_lshl_add_u64 v[150:151], v[248:249], 0, s[6:7]
	s_mov_b32 m0, s38
	s_nop 0
	global_load_lds_dwordx4 v[150:151], off
	v_lshl_add_u64 v[150:151], v[250:251], 0, s[6:7]
	s_mov_b32 m0, s39
	s_nop 0
	global_load_lds_dwordx4 v[150:151], off
	s_waitcnt vmcnt(8)
	s_waitcnt lgkmcnt(0)
	s_setprio 1
	s_barrier
	v_mfma_f32_16x16x32_bf16 v[60:63], v[136:139], v[202:205], v[60:63]
	v_mfma_f32_16x16x32_bf16 v[52:55], v[178:181], v[202:205], v[52:55]
	v_mfma_f32_16x16x32_bf16 v[44:47], v[136:139], v[210:213], v[44:47]
	v_mfma_f32_16x16x32_bf16 v[36:39], v[178:181], v[210:213], v[36:39]
	v_mfma_f32_16x16x32_bf16 v[28:31], v[136:139], v[218:221], v[28:31]
	v_mfma_f32_16x16x32_bf16 v[20:23], v[178:181], v[218:221], v[20:23]
	v_mfma_f32_16x16x32_bf16 v[12:15], v[136:139], v[226:229], v[12:15]
	v_mfma_f32_16x16x32_bf16 v[4:7], v[178:181], v[226:229], v[4:7]
	v_mfma_f32_16x16x32_bf16 v[60:63], v[174:177], v[206:209], v[60:63]
	v_mfma_f32_16x16x32_bf16 v[52:55], v[182:185], v[206:209], v[52:55]
	v_mfma_f32_16x16x32_bf16 v[44:47], v[174:177], v[214:217], v[44:47]
	v_mfma_f32_16x16x32_bf16 v[36:39], v[182:185], v[214:217], v[36:39]
	v_mfma_f32_16x16x32_bf16 v[28:31], v[174:177], v[222:225], v[28:31]
	v_mfma_f32_16x16x32_bf16 v[20:23], v[182:185], v[222:225], v[20:23]
	v_mfma_f32_16x16x32_bf16 v[12:15], v[174:177], v[236:239], v[12:15]
	v_mfma_f32_16x16x32_bf16 v[4:7], v[182:185], v[236:239], v[4:7]
	s_setprio 0
	s_setprio 1
	v_mfma_f32_16x16x32_bf16 v[56:59], v[186:189], v[202:205], v[56:59]
	v_mfma_f32_16x16x32_bf16 v[48:51], v[194:197], v[202:205], v[48:51]
	v_mfma_f32_16x16x32_bf16 v[40:43], v[186:189], v[210:213], v[40:43]
	v_mfma_f32_16x16x32_bf16 v[32:35], v[194:197], v[210:213], v[32:35]
	v_mfma_f32_16x16x32_bf16 v[24:27], v[186:189], v[218:221], v[24:27]
	v_mfma_f32_16x16x32_bf16 v[16:19], v[194:197], v[218:221], v[16:19]
	v_mfma_f32_16x16x32_bf16 v[8:11], v[186:189], v[226:229], v[8:11]
	v_mfma_f32_16x16x32_bf16 v[0:3], v[194:197], v[226:229], v[0:3]
	v_mfma_f32_16x16x32_bf16 v[56:59], v[190:193], v[206:209], v[56:59]
	v_mfma_f32_16x16x32_bf16 v[48:51], v[198:201], v[206:209], v[48:51]
	v_mfma_f32_16x16x32_bf16 v[40:43], v[190:193], v[214:217], v[40:43]
	v_mfma_f32_16x16x32_bf16 v[32:35], v[198:201], v[214:217], v[32:35]
	v_mfma_f32_16x16x32_bf16 v[24:27], v[190:193], v[222:225], v[24:27]
	v_mfma_f32_16x16x32_bf16 v[16:19], v[198:201], v[222:225], v[16:19]
	v_mfma_f32_16x16x32_bf16 v[8:11], v[190:193], v[236:239], v[8:11]
	v_mfma_f32_16x16x32_bf16 v[0:3], v[198:201], v[236:239], v[0:3]
	s_barrier
	s_setprio 0
	s_add_i32 s50, s50, 2
	s_add_u32 s24, s24, 0x100
	s_addc_u32 s25, s25, 0
	s_add_u32 s48, s48, 0x100
	s_addc_u32 s49, s49, 0
	s_cmp_gt_u32 s50, 13
	s_cbranch_scc1 .Lpeel_done_g4
	.p2align	6

; #define PG8_STAGE(bufoff, gbase, voff) do { _Pragma("unroll") for (int _i = 0; _i < 2; ++_i) \
;         __builtin_amdgcn_global_load_lds((const unsigned*)((const char*)(gbase) + (voff)[_i]), (PG8_LAS unsigned*)(lds + (bufoff) + ldsw + _i * 8192), 16, 0, 0); } while (0)
; #define PG8_LDA(dst, b, h) do { _Pragma("unroll") for (int m = 0; m < 4; ++m) _Pragma("unroll") for (int k = 0; k < 2; ++k) dst[m][k] = *(const PG8_LAS bf16x8*)(lds + PG8_SA(b, h) + aoff + m * 2048 + k * 1024); } while (0)
; #define PG8_LDB(dst, b, h) do { _Pragma("unroll") for (int n = 0; n < 2; ++n) _Pragma("unroll") for (int k = 0; k < 2; ++k) dst[n][k] = *(const PG8_LAS bf16x8*)(lds + PG8_SB(b, h) + boff + n * 2048 + k * 1024); } while (0)
; #define PG8_MMA(ai, bj, At, Bt) do { __builtin_amdgcn_s_setprio(1); _Pragma("unroll") for (int m = 0; m < 4; ++m) _Pragma("unroll") for (int n = 0; n < 2; ++n) _Pragma("unroll") for (int k = 0; k < 2; ++k) \
;         acc[ai][bj][m][n] = __builtin_amdgcn_mfma_f32_16x16x32_bf16(Bt[n][k], At[m][k], acc[ai][bj][m][n], 0, 0, 0); __builtin_amdgcn_s_setprio(0); } while (0)
; #define PG8_BAR __builtin_amdgcn_s_barrier()
; template <class Epi, class Sched, bool ALIGN_EPI = false, bool SP2 = false>
; __device__ __forceinline__ void gemm_phase(PG8_LAS unsigned char* lds, const Gemm g, const Sched& S, const Epi& E) {
;     ...
;         const bool has_next = S.next(ui + 1, nxt);
;         const char* nA = has_next ? (const char*)g.A + (size_t)nxt.pm * tstep : cA; const char* nB = has_next ? (const char*)g.Bt + (size_t)nxt.pn * tstep : cB;
;         for (int t = 0; t < nt; t += 2) {
;             const bool last = (t == nt - 2);
;             const char* a1 = cA + (size_t)(t + 1) * kstep;
;             const char* a2 = last ? nA : cA + (size_t)(t + 2) * kstep; const char* b2 = last ? nB : cB + (size_t)(t + 2) * kstep;
;             const char* a3 = a2 + kstep; const char* b3 = b2 + kstep;
;             if (last && has_next) S.a_ready(nxt);
;             if constexpr (SP2) {
;             PG8_LDB(B0, 0, 0); PG8_LDB(B1, 0, 1); PG8_SCHED; PG8_LDA(At, 0, 0); PG8_STAGE(PG8_SA(1, 1), a1 + hstep, voffA);
;             PG8_WAIT_V(8); PG8_WAIT_L(0); PG8_BAR; PG8_MMA(0, 0, At, B0); PG8_MMA(0, 1, At, B1); PG8_BAR; PG8_SCHED;
;             PG8_LDA(At, 0, 1); PG8_STAGE(PG8_SB(0, 0), b2, voffB); PG8_STAGE(PG8_SB(0, 1), b2 + hstep, voffB); PG8_STAGE(PG8_SA(0, 0), a2, voffA);
.LBB0_1441:
	s_add_u32 s6, s26, 0xb0080
	s_addc_u32 s7, s27, 0
	s_add_u32 s48, s10, 0x100
	s_addc_u32 s49, s11, 0
	s_mov_b32 s50, -2
	ds_read_b128 v[128:131], v213
	ds_read_b128 v[132:135], v213 offset:1024
	ds_read_b128 v[136:139], v213 offset:2048
	ds_read_b128 v[140:143], v213 offset:3072
	ds_read_b128 v[144:147], v214
	ds_read_b128 v[148:151], v214 offset:1024
	ds_read_b128 v[172:175], v214 offset:2048
	ds_read_b128 v[176:179], v214 offset:3072
	s_add_u32 s10, s6, 0xfff50080
	s_addc_u32 s11, s7, -1
	s_cmp_eq_u32 s50, 40
	s_cselect_b32 s27, s23, s11
	s_cselect_b32 s26, s22, s10
	s_cselect_b32 s11, s25, s49
	s_cselect_b32 s10, s24, s48
	v_lshl_add_u64 v[162:163], s[6:7], 0, v[154:155]
	s_add_i32 m0, s29, 0xc000
	ds_read_b128 v[180:183], v215
	ds_read_b128 v[184:187], v215 offset:1024
	ds_read_b128 v[188:191], v215 offset:2048
	ds_read_b128 v[192:195], v215 offset:3072
	ds_read_b128 v[196:199], v215 offset:4096
	ds_read_b128 v[200:203], v215 offset:5120
	ds_read_b128 v[204:207], v215 offset:6144
	ds_read_b128 v[220:223], v215 offset:7168
	global_load_lds_dwordx4 v[162:163], off
	v_lshl_add_u64 v[162:163], s[6:7], 0, v[156:157]
	s_add_i32 m0, s29, 0xe000
	s_nop 0
	global_load_lds_dwordx4 v[162:163], off
	s_waitcnt vmcnt(8)
	s_waitcnt lgkmcnt(0)
	s_setprio 1
	s_barrier
	v_mfma_f32_16x16x32_bf16 v[124:127], v[128:131], v[180:183], 0
	v_mfma_f32_16x16x32_bf16 v[120:123], v[136:139], v[180:183], 0
	v_mfma_f32_16x16x32_bf16 v[108:111], v[128:131], v[188:191], 0
	v_mfma_f32_16x16x32_bf16 v[104:107], v[136:139], v[188:191], 0
	v_mfma_f32_16x16x32_bf16 v[92:95], v[128:131], v[196:199], 0
	v_mfma_f32_16x16x32_bf16 v[88:91], v[136:139], v[196:199], 0
	v_mfma_f32_16x16x32_bf16 v[76:79], v[128:131], v[204:207], 0
	v_mfma_f32_16x16x32_bf16 v[72:75], v[136:139], v[204:207], 0
	v_mfma_f32_16x16x32_bf16 v[124:127], v[132:135], v[184:187], v[124:127]
	v_mfma_f32_16x16x32_bf16 v[120:123], v[140:143], v[184:187], v[120:123]
	v_mfma_f32_16x16x32_bf16 v[108:111], v[132:135], v[192:195], v[108:111]
	v_mfma_f32_16x16x32_bf16 v[104:107], v[140:143], v[192:195], v[104:107]
	v_mfma_f32_16x16x32_bf16 v[92:95], v[132:135], v[200:203], v[92:95]
	v_mfma_f32_16x16x32_bf16 v[88:91], v[140:143], v[200:203], v[88:91]
	v_mfma_f32_16x16x32_bf16 v[76:79], v[132:135], v[220:223], v[76:79]
	v_mfma_f32_16x16x32_bf16 v[72:75], v[140:143], v[220:223], v[72:75]
	s_setprio 0
	s_setprio 1
	v_mfma_f32_16x16x32_bf16 v[116:119], v[144:147], v[180:183], 0
	v_mfma_f32_16x16x32_bf16 v[112:115], v[172:175], v[180:183], 0
	v_mfma_f32_16x16x32_bf16 v[100:103], v[144:147], v[188:191], 0
	v_mfma_f32_16x16x32_bf16 v[96:99], v[172:175], v[188:191], 0
	v_mfma_f32_16x16x32_bf16 v[84:87], v[144:147], v[196:199], 0
	v_mfma_f32_16x16x32_bf16 v[80:83], v[172:175], v[196:199], 0
	v_mfma_f32_16x16x32_bf16 v[68:71], v[144:147], v[204:207], 0
	v_mfma_f32_16x16x32_bf16 v[64:67], v[172:175], v[204:207], 0
	v_mfma_f32_16x16x32_bf16 v[116:119], v[148:151], v[184:187], v[116:119]
	v_mfma_f32_16x16x32_bf16 v[112:115], v[176:179], v[184:187], v[112:115]
	v_mfma_f32_16x16x32_bf16 v[100:103], v[148:151], v[192:195], v[100:103]
	v_mfma_f32_16x16x32_bf16 v[96:99], v[176:179], v[192:195], v[96:99]
	v_mfma_f32_16x16x32_bf16 v[84:87], v[148:151], v[200:203], v[84:87]
	v_mfma_f32_16x16x32_bf16 v[80:83], v[176:179], v[200:203], v[80:83]
	v_mfma_f32_16x16x32_bf16 v[68:71], v[148:151], v[220:223], v[68:71]
	v_mfma_f32_16x16x32_bf16 v[64:67], v[176:179], v[220:223], v[64:67]
	s_barrier
	s_setprio 0
	s_add_i32 s51, s41, s28
	v_lshl_add_u64 v[162:163], s[10:11], 0, v[166:167]
	s_mov_b32 m0, s51
	ds_read_b128 v[180:183], v215 offset:16384
	ds_read_b128 v[184:187], v215 offset:17408
	ds_read_b128 v[188:191], v215 offset:18432
	ds_read_b128 v[192:195], v215 offset:19456
	ds_read_b128 v[196:199], v215 offset:20480
	ds_read_b128 v[200:203], v215 offset:21504
	ds_read_b128 v[204:207], v215 offset:22528
	ds_read_b128 v[220:223], v215 offset:23552
	global_load_lds_dwordx4 v[162:163], off
	s_add_i32 m0, s51, 0x2000
	s_add_u32 s52, s10, 0xb0000
	v_lshl_add_u64 v[208:209], s[10:11], 0, v[170:171]
	s_addc_u32 s53, s11, 0
	s_add_i32 s51, s42, s28
	global_load_lds_dwordx4 v[208:209], off
	v_lshl_add_u64 v[224:225], s[52:53], 0, v[166:167]
	s_mov_b32 m0, s51
	v_lshl_add_u64 v[226:227], s[26:27], 0, v[168:169]
	global_load_lds_dwordx4 v[224:225], off
	v_lshl_add_u64 v[224:225], s[52:53], 0, v[170:171]
	s_add_i32 m0, s51, 0x2000
	s_nop 0
	global_load_lds_dwordx4 v[224:225], off
	v_lshl_add_u64 v[224:225], s[26:27], 0, v[164:165]
	s_mov_b32 m0, s29
	s_nop 0
	global_load_lds_dwordx4 v[224:225], off
	s_mov_b32 m0, s30
	s_nop 0
	global_load_lds_dwordx4 v[226:227], off
	s_waitcnt vmcnt(8)
	s_waitcnt lgkmcnt(0)
	s_setprio 1
	s_barrier
; #define PG8_STAGE(bufoff, gbase, voff) do { _Pragma("unroll") for (int _i = 0; _i < 2; ++_i) \
;         __builtin_amdgcn_global_load_lds((const unsigned*)((const char*)(gbase) + (voff)[_i]), (PG8_LAS unsigned*)(lds + (bufoff) + ldsw + _i * 8192), 16, 0, 0); } while (0)
; #define PG8_LDA(dst, b, h) do { _Pragma("unroll") for (int m = 0; m < 4; ++m) _Pragma("unroll") for (int k = 0; k < 2; ++k) dst[m][k] = *(const PG8_LAS bf16x8*)(lds + PG8_SA(b, h) + aoff + m * 2048 + k * 1024); } while (0)
; #define PG8_LDB(dst, b, h) do { _Pragma("unroll") for (int n = 0; n < 2; ++n) _Pragma("unroll") for (int k = 0; k < 2; ++k) dst[n][k] = *(const PG8_LAS bf16x8*)(lds + PG8_SB(b, h) + boff + n * 2048 + k * 1024); } while (0)
; #define PG8_MMA(ai, bj, At, Bt) do { __builtin_amdgcn_s_setprio(1); _Pragma("unroll") for (int m = 0; m < 4; ++m) _Pragma("unroll") for (int n = 0; n < 2; ++n) _Pragma("unroll") for (int k = 0; k < 2; ++k) \
;         acc[ai][bj][m][n] = __builtin_amdgcn_mfma_f32_16x16x32_bf16(Bt[n][k], At[m][k], acc[ai][bj][m][n], 0, 0, 0); __builtin_amdgcn_s_setprio(0); } while (0)
; #define PG8_WAIT_V(n) asm volatile("s_waitcnt vmcnt(" #n ")" ::: "memory")
; #define PG8_WAIT_L(n) asm volatile("s_waitcnt lgkmcnt(" #n ")" ::: "memory")
; #define PG8_BAR __builtin_amdgcn_s_barrier()
; #define PG8_SCHED __builtin_amdgcn_sched_barrier(0)
; template <class Epi, class Sched, bool ALIGN_EPI = false, bool SP2 = false>
; __device__ __forceinline__ void gemm_phase(PG8_LAS unsigned char* lds, const Gemm g, const Sched& S, const Epi& E) {
;     ...
;             PG8_WAIT_V(8); PG8_WAIT_L(0); PG8_BAR; PG8_MMA(1, 0, At, B0); PG8_MMA(1, 1, At, B1); PG8_BAR; PG8_SCHED;
;             PG8_LDB(B0, 1, 0); PG8_LDB(B1, 1, 1); PG8_SCHED; PG8_LDA(At, 1, 0); PG8_STAGE(PG8_SA(0, 1), a2 + hstep, voffA);
;             PG8_WAIT_V(8); PG8_WAIT_L(0); PG8_BAR; PG8_MMA(0, 0, At, B0); PG8_MMA(0, 1, At, B1); PG8_BAR; PG8_SCHED;
	v_mfma_f32_16x16x32_bf16 v[60:63], v[128:131], v[180:183], 0
	v_mfma_f32_16x16x32_bf16 v[56:59], v[136:139], v[180:183], 0
	v_mfma_f32_16x16x32_bf16 v[44:47], v[128:131], v[188:191], 0
	v_mfma_f32_16x16x32_bf16 v[40:43], v[136:139], v[188:191], 0
	v_mfma_f32_16x16x32_bf16 v[28:31], v[128:131], v[196:199], 0
	v_mfma_f32_16x16x32_bf16 v[24:27], v[136:139], v[196:199], 0
	v_mfma_f32_16x16x32_bf16 v[12:15], v[128:131], v[204:207], 0
	v_mfma_f32_16x16x32_bf16 v[8:11], v[136:139], v[204:207], 0
	v_mfma_f32_16x16x32_bf16 v[60:63], v[132:135], v[184:187], v[60:63]
	v_mfma_f32_16x16x32_bf16 v[56:59], v[140:143], v[184:187], v[56:59]
	v_mfma_f32_16x16x32_bf16 v[44:47], v[132:135], v[192:195], v[44:47]
	v_mfma_f32_16x16x32_bf16 v[40:43], v[140:143], v[192:195], v[40:43]
	v_mfma_f32_16x16x32_bf16 v[28:31], v[132:135], v[200:203], v[28:31]
	v_mfma_f32_16x16x32_bf16 v[24:27], v[140:143], v[200:203], v[24:27]
	v_mfma_f32_16x16x32_bf16 v[12:15], v[132:135], v[220:223], v[12:15]
	v_mfma_f32_16x16x32_bf16 v[8:11], v[140:143], v[220:223], v[8:11]
	s_setprio 0
	s_setprio 1
	v_mfma_f32_16x16x32_bf16 v[52:55], v[144:147], v[180:183], 0
	v_mfma_f32_16x16x32_bf16 v[48:51], v[172:175], v[180:183], 0
	v_mfma_f32_16x16x32_bf16 v[36:39], v[144:147], v[188:191], 0
	v_mfma_f32_16x16x32_bf16 v[32:35], v[172:175], v[188:191], 0
	v_mfma_f32_16x16x32_bf16 v[20:23], v[144:147], v[196:199], 0
	v_mfma_f32_16x16x32_bf16 v[16:19], v[172:175], v[196:199], 0
	v_mfma_f32_16x16x32_bf16 v[4:7], v[144:147], v[204:207], 0
	v_mfma_f32_16x16x32_bf16 v[0:3], v[172:175], v[204:207], 0
	v_mfma_f32_16x16x32_bf16 v[52:55], v[148:151], v[184:187], v[52:55]
	v_mfma_f32_16x16x32_bf16 v[48:51], v[176:179], v[184:187], v[48:51]
	v_mfma_f32_16x16x32_bf16 v[36:39], v[148:151], v[192:195], v[36:39]
	v_mfma_f32_16x16x32_bf16 v[32:35], v[176:179], v[192:195], v[32:35]
	v_mfma_f32_16x16x32_bf16 v[20:23], v[148:151], v[200:203], v[20:23]
	v_mfma_f32_16x16x32_bf16 v[16:19], v[176:179], v[200:203], v[16:19]
	v_mfma_f32_16x16x32_bf16 v[4:7], v[148:151], v[220:223], v[4:7]
	v_mfma_f32_16x16x32_bf16 v[0:3], v[176:179], v[220:223], v[0:3]
	s_barrier
	s_setprio 0
	s_add_i32 s51, 0, 0x18000
	s_add_i32 s52, 0, 0x1c000
	v_add_u32_e32 v140, s51, v211
	v_add_u32_e32 v176, s52, v211
	ds_read_b128 v[128:131], v140
	ds_read_b128 v[132:135], v140 offset:1024
	ds_read_b128 v[136:139], v140 offset:2048
	ds_read_b128 v[140:143], v140 offset:3072
	ds_read_b128 v[144:147], v176
	ds_read_b128 v[148:151], v176 offset:1024
	ds_read_b128 v[172:175], v176 offset:2048
	ds_read_b128 v[176:179], v176 offset:3072
	s_add_u32 s26, s26, 0xb0000
	s_addc_u32 s27, s27, 0
	s_mov_b32 m0, s31
	v_lshl_add_u64 v[228:229], s[26:27], 0, v[164:165]
	ds_read_b128 v[180:183], v215 offset:32768
	ds_read_b128 v[184:187], v215 offset:33792
	ds_read_b128 v[188:191], v215 offset:34816
	ds_read_b128 v[192:195], v215 offset:35840
	ds_read_b128 v[196:199], v215 offset:36864
	ds_read_b128 v[200:203], v215 offset:37888
	ds_read_b128 v[204:207], v215 offset:38912
	ds_read_b128 v[220:223], v215 offset:39936
	global_load_lds_dwordx4 v[228:229], off
	v_lshl_add_u64 v[228:229], s[26:27], 0, v[168:169]
	s_mov_b32 m0, s33
	s_nop 0
	global_load_lds_dwordx4 v[228:229], off
	s_waitcnt vmcnt(8)
	s_waitcnt lgkmcnt(0)
	s_setprio 1
	s_barrier
	v_mfma_f32_16x16x32_bf16 v[124:127], v[128:131], v[180:183], v[124:127]
	v_mfma_f32_16x16x32_bf16 v[120:123], v[136:139], v[180:183], v[120:123]
	v_mfma_f32_16x16x32_bf16 v[108:111], v[128:131], v[188:191], v[108:111]
	v_mfma_f32_16x16x32_bf16 v[104:107], v[136:139], v[188:191], v[104:107]
	v_mfma_f32_16x16x32_bf16 v[92:95], v[128:131], v[196:199], v[92:95]
	v_mfma_f32_16x16x32_bf16 v[88:91], v[136:139], v[196:199], v[88:91]
	v_mfma_f32_16x16x32_bf16 v[76:79], v[128:131], v[204:207], v[76:79]
	v_mfma_f32_16x16x32_bf16 v[72:75], v[136:139], v[204:207], v[72:75]
	v_mfma_f32_16x16x32_bf16 v[124:127], v[132:135], v[184:187], v[124:127]
	v_mfma_f32_16x16x32_bf16 v[120:123], v[140:143], v[184:187], v[120:123]
	v_mfma_f32_16x16x32_bf16 v[108:111], v[132:135], v[192:195], v[108:111]
	v_mfma_f32_16x16x32_bf16 v[104:107], v[140:143], v[192:195], v[104:107]
	v_mfma_f32_16x16x32_bf16 v[92:95], v[132:135], v[200:203], v[92:95]
	v_mfma_f32_16x16x32_bf16 v[88:91], v[140:143], v[200:203], v[88:91]
	v_mfma_f32_16x16x32_bf16 v[76:79], v[132:135], v[220:223], v[76:79]
	v_mfma_f32_16x16x32_bf16 v[72:75], v[140:143], v[220:223], v[72:75]
	s_setprio 0
	s_setprio 1
	v_mfma_f32_16x16x32_bf16 v[116:119], v[144:147], v[180:183], v[116:119]
	v_mfma_f32_16x16x32_bf16 v[112:115], v[172:175], v[180:183], v[112:115]
	v_mfma_f32_16x16x32_bf16 v[100:103], v[144:147], v[188:191], v[100:103]
	v_mfma_f32_16x16x32_bf16 v[96:99], v[172:175], v[188:191], v[96:99]
	v_mfma_f32_16x16x32_bf16 v[84:87], v[144:147], v[196:199], v[84:87]
	v_mfma_f32_16x16x32_bf16 v[80:83], v[172:175], v[196:199], v[80:83]
	v_mfma_f32_16x16x32_bf16 v[68:71], v[144:147], v[204:207], v[68:71]
	v_mfma_f32_16x16x32_bf16 v[64:67], v[172:175], v[204:207], v[64:67]
	v_mfma_f32_16x16x32_bf16 v[116:119], v[148:151], v[184:187], v[116:119]
	v_mfma_f32_16x16x32_bf16 v[112:115], v[176:179], v[184:187], v[112:115]
	v_mfma_f32_16x16x32_bf16 v[100:103], v[148:151], v[192:195], v[100:103]
	v_mfma_f32_16x16x32_bf16 v[96:99], v[176:179], v[192:195], v[96:99]
	v_mfma_f32_16x16x32_bf16 v[84:87], v[148:151], v[200:203], v[84:87]
	v_mfma_f32_16x16x32_bf16 v[80:83], v[176:179], v[200:203], v[80:83]
	v_mfma_f32_16x16x32_bf16 v[68:71], v[148:151], v[220:223], v[68:71]
	v_mfma_f32_16x16x32_bf16 v[64:67], v[176:179], v[220:223], v[64:67]
	s_barrier
; #define PG8_STAGE(bufoff, gbase, voff) do { _Pragma("unroll") for (int _i = 0; _i < 2; ++_i) \
;         __builtin_amdgcn_global_load_lds((const unsigned*)((const char*)(gbase) + (voff)[_i]), (PG8_LAS unsigned*)(lds + (bufoff) + ldsw + _i * 8192), 16, 0, 0); } while (0)
; #define PG8_LDA(dst, b, h) do { _Pragma("unroll") for (int m = 0; m < 4; ++m) _Pragma("unroll") for (int k = 0; k < 2; ++k) dst[m][k] = *(const PG8_LAS bf16x8*)(lds + PG8_SA(b, h) + aoff + m * 2048 + k * 1024); } while (0)
; #define PG8_MMA(ai, bj, At, Bt) do { __builtin_amdgcn_s_setprio(1); _Pragma("unroll") for (int m = 0; m < 4; ++m) _Pragma("unroll") for (int n = 0; n < 2; ++n) _Pragma("unroll") for (int k = 0; k < 2; ++k) \
;         acc[ai][bj][m][n] = __builtin_amdgcn_mfma_f32_16x16x32_bf16(Bt[n][k], At[m][k], acc[ai][bj][m][n], 0, 0, 0); __builtin_amdgcn_s_setprio(0); } while (0)
; #define PG8_WAIT_V(n) asm volatile("s_waitcnt vmcnt(" #n ")" ::: "memory")
; #define PG8_WAIT_L(n) asm volatile("s_waitcnt lgkmcnt(" #n ")" ::: "memory")
; #define PG8_BAR __builtin_amdgcn_s_barrier()
; #define PG8_SCHED __builtin_amdgcn_sched_barrier(0)
; template <class Epi, class Sched, bool ALIGN_EPI = false, bool SP2 = false>
; __device__ __forceinline__ void gemm_phase(PG8_LAS unsigned char* lds, const Gemm g, const Sched& S, const Epi& E) {
;     ...
;         for (int t = 0; t < nt; t += 2) {
;             const bool last = (t == nt - 2);
;     ...
;             PG8_LDA(At, 1, 1); PG8_STAGE(PG8_SB(1, 0), b3, voffB); PG8_STAGE(PG8_SB(1, 1), b3 + hstep, voffB); PG8_STAGE(PG8_SA(1, 0), a3, voffA);
;             PG8_WAIT_V(8); PG8_WAIT_L(0); PG8_BAR; PG8_MMA(1, 0, At, B0); PG8_MMA(1, 1, At, B1); PG8_BAR; PG8_SCHED;
	s_setprio 0
	s_add_i32 s26, s51, s28
	v_lshl_add_u64 v[162:163], v[162:163], 0, s[18:19]
	s_mov_b32 m0, s26
	ds_read_b128 v[180:183], v215 offset:49152
	ds_read_b128 v[184:187], v215 offset:50176
	ds_read_b128 v[188:191], v215 offset:51200
	ds_read_b128 v[192:195], v215 offset:52224
	ds_read_b128 v[196:199], v215 offset:53248
	ds_read_b128 v[200:203], v215 offset:54272
	ds_read_b128 v[204:207], v215 offset:55296
	ds_read_b128 v[220:223], v215 offset:56320
	global_load_lds_dwordx4 v[162:163], off
	s_add_i32 m0, s26, 0x2000
	s_add_u32 s10, s10, 0xb0080
	v_lshl_add_u64 v[162:163], v[208:209], 0, s[18:19]
	s_addc_u32 s11, s11, 0
	s_add_i32 s26, s52, s28
	global_load_lds_dwordx4 v[162:163], off
	v_lshl_add_u64 v[162:163], s[10:11], 0, v[166:167]
	s_mov_b32 m0, s26
	s_nop 0
	global_load_lds_dwordx4 v[162:163], off
	v_lshl_add_u64 v[162:163], s[10:11], 0, v[170:171]
	s_add_i32 m0, s26, 0x2000
	s_nop 0
	global_load_lds_dwordx4 v[162:163], off
	v_lshl_add_u64 v[162:163], v[224:225], 0, s[18:19]
	s_mov_b32 m0, s37
	s_nop 0
	global_load_lds_dwordx4 v[162:163], off
	v_lshl_add_u64 v[162:163], v[226:227], 0, s[18:19]
	s_mov_b32 m0, s38
	s_nop 0
	global_load_lds_dwordx4 v[162:163], off
	s_waitcnt vmcnt(8)
	s_waitcnt lgkmcnt(0)
	s_setprio 1
	s_barrier
	v_mfma_f32_16x16x32_bf16 v[60:63], v[128:131], v[180:183], v[60:63]
	v_mfma_f32_16x16x32_bf16 v[56:59], v[136:139], v[180:183], v[56:59]
	v_mfma_f32_16x16x32_bf16 v[44:47], v[128:131], v[188:191], v[44:47]
	v_mfma_f32_16x16x32_bf16 v[40:43], v[136:139], v[188:191], v[40:43]
	v_mfma_f32_16x16x32_bf16 v[28:31], v[128:131], v[196:199], v[28:31]
	v_mfma_f32_16x16x32_bf16 v[24:27], v[136:139], v[196:199], v[24:27]
	v_mfma_f32_16x16x32_bf16 v[12:15], v[128:131], v[204:207], v[12:15]
	v_mfma_f32_16x16x32_bf16 v[8:11], v[136:139], v[204:207], v[8:11]
	v_mfma_f32_16x16x32_bf16 v[60:63], v[132:135], v[184:187], v[60:63]
	v_mfma_f32_16x16x32_bf16 v[56:59], v[140:143], v[184:187], v[56:59]
	v_mfma_f32_16x16x32_bf16 v[44:47], v[132:135], v[192:195], v[44:47]
	v_mfma_f32_16x16x32_bf16 v[40:43], v[140:143], v[192:195], v[40:43]
	v_mfma_f32_16x16x32_bf16 v[28:31], v[132:135], v[200:203], v[28:31]
	v_mfma_f32_16x16x32_bf16 v[24:27], v[140:143], v[200:203], v[24:27]
	v_mfma_f32_16x16x32_bf16 v[12:15], v[132:135], v[220:223], v[12:15]
	v_mfma_f32_16x16x32_bf16 v[8:11], v[140:143], v[220:223], v[8:11]
	s_setprio 0
	s_setprio 1
	v_mfma_f32_16x16x32_bf16 v[52:55], v[144:147], v[180:183], v[52:55]
	v_mfma_f32_16x16x32_bf16 v[48:51], v[172:175], v[180:183], v[48:51]
	v_mfma_f32_16x16x32_bf16 v[36:39], v[144:147], v[188:191], v[36:39]
	v_mfma_f32_16x16x32_bf16 v[32:35], v[172:175], v[188:191], v[32:35]
	v_mfma_f32_16x16x32_bf16 v[20:23], v[144:147], v[196:199], v[20:23]
	v_mfma_f32_16x16x32_bf16 v[16:19], v[172:175], v[196:199], v[16:19]
	v_mfma_f32_16x16x32_bf16 v[4:7], v[144:147], v[204:207], v[4:7]
	v_mfma_f32_16x16x32_bf16 v[0:3], v[172:175], v[204:207], v[0:3]
	v_mfma_f32_16x16x32_bf16 v[52:55], v[148:151], v[184:187], v[52:55]
	v_mfma_f32_16x16x32_bf16 v[48:51], v[176:179], v[184:187], v[48:51]
	v_mfma_f32_16x16x32_bf16 v[36:39], v[148:151], v[192:195], v[36:39]
	v_mfma_f32_16x16x32_bf16 v[32:35], v[176:179], v[192:195], v[32:35]
	v_mfma_f32_16x16x32_bf16 v[20:23], v[148:151], v[200:203], v[20:23]
	v_mfma_f32_16x16x32_bf16 v[16:19], v[176:179], v[200:203], v[16:19]
	v_mfma_f32_16x16x32_bf16 v[4:7], v[148:151], v[220:223], v[4:7]
	v_mfma_f32_16x16x32_bf16 v[0:3], v[176:179], v[220:223], v[0:3]
	s_barrier
	s_setprio 0
	s_add_i32 s50, s50, 2
	s_add_u32 s6, s6, 0x100
	s_addc_u32 s7, s7, 0
	s_add_u32 s48, s48, 0x100
	s_addc_u32 s49, s49, 0
	s_cmp_gt_u32 s50, 41
	s_cbranch_scc1 .Lpeel_done_g5
	.p2align	6
